# o44 plus reciprocal-multiply for the 1/sum of the merged prompt softmax (same as the other division sites)
# baseline (speedup 1.0000x reference)
; #define LAS __attribute__((address_space(3)))
; template <int WT, class Epi>
; DEV void gemm_tile(const bf16_t* __restrict__ A, int lda, const bf16_t* __restrict__ Bt, int ldb, int K, unsigned char* lds, const Epi& epi) {
;     constexpr int FI = WT / 16;
;     constexpr int OPB = 2 * WT * 128;
;     constexpr int STB = 2 * OPB;
;     int tid = threadIdx.x & 255; asm volatile("" : "+v"(tid)); const int lane = tid & 63, wid = tid >> 6;
;     const int wr = wid >> 1, wc = wid & 1, fr = lane & 15, fq = lane >> 4;
;     f32x4 acc[FI][FI];
; #pragma unroll
;     for (int i = 0; i < FI; ++i)
; #pragma unroll
;         for (int j = 0; j < FI; ++j) acc[i][j] = (f32x4){0.f, 0.f, 0.f, 0.f};
;     const int lrow = tid >> 3, lcs = (tid & 7) ^ (lrow & 7);
;     const bf16_t* ap = A + (size_t)lrow * lda + lcs * 8;
;     const bf16_t* bp = Bt + (size_t)lrow * ldb + lcs * 8;
;     const unsigned l3a = (unsigned)(size_t)(LAS unsigned char*)lds;
;     const int nk = K >> 6;
;     ...
;     constexpr int NSTG = 65536 / STB;
; #pragma unroll
;     for (int s_ = 0; s_ < NSTG - 1; ++s_) if (s_ < nk) GLDS_STAGE(s_ * STB, s_);
;     const int aoff = (wr * WT + fr) * 128, boff = OPB + (wc * WT + fr) * 128, sw = fr & 7;
;     int cur = 0, nxt = (NSTG - 1) * STB;
;     for (int kt = 0; kt < nk; ++kt) {
;         if (NSTG == 4 && kt + 2 < nk) { if (FI == 2) asm volatile("s_waitcnt vmcnt(8)" ::: "memory"); else asm volatile("s_waitcnt vmcnt(0)" ::: "memory"); }
;         else asm volatile("s_waitcnt vmcnt(0)" ::: "memory");
;         __syncthreads();
;         if (kt + NSTG - 1 < nk) GLDS_STAGE(nxt, kt + NSTG - 1);
; #pragma unroll
;         for (int kh = 0; kh < 2; ++kh) {
;             bf16x8 af[FI], bfr[FI];
;             const int ch = ((kh * 4 + fq) ^ sw) << 4;
; #pragma unroll
;             for (int i = 0; i < FI; ++i) { af[i] = *(const bf16x8*)(lds + cur + aoff + i * 2048 + ch); bfr[i] = *(const bf16x8*)(lds + cur + boff + i * 2048 + ch); }
; #pragma unroll
;             for (int mi = 0; mi < FI; ++mi)
; #pragma unroll
;                 for (int ni = 0; ni < FI; ++ni) acc[mi][ni] = __builtin_amdgcn_mfma_f32_16x16x32_bf16(bfr[ni], af[mi], acc[mi][ni], 0, 0, 0);
; __global__ void __launch_bounds__(512) hymba_fwd(Params p) {
;     ...
;         VLOOP(t, NS1) { const int bhd = t >> 5, v = t & 31, mt = v >> 1, nt = v & 1, b = bhd >> 2, hd = bhd & 3;
.LBB0_1295:
	s_ashr_i32 s14, s86, 7
	s_lshl_b32 s4, s86, 6
	s_lshl_b32 s76, s86, 7
	v_mov_b32_e32 v7, v1
	s_lshl_b32 s78, s14, 11
	s_and_b32 s79, s4, 0x780
	s_lshl_b32 s15, s86, 5
	s_and_b32 s77, s76, 0x80
	s_lshl_b32 s14, s14, 8
	s_or_b32 s76, s78, s79
	v_ashrrev_i32_e32 v13, 3, v7
	s_and_b32 s4, s15, 0xc00
	s_or_b32 s14, s14, s77
	v_lshrrev_b32_e32 v4, 4, v7
	v_and_b32_e32 v6, 15, v7
	v_ashrrev_i32_e32 v15, 1, v7
	v_lshlrev_b32_e32 v16, 7, v7
	v_and_b32_e32 v17, 7, v7
	v_mad_i64_i32 v[8:9], s[78:79], s76, v12, v[132:133]
	v_xor_b32_e32 v18, v13, v7
	v_lshlrev_b32_e32 v14, 4, v7
	v_mad_i64_i32 v[10:11], s[78:79], s14, v12, v[168:169]
	v_and_or_b32 v6, v15, s85, v6
	v_and_b32_e32 v15, 0x2780, v16
	v_bitop3_b32 v4, v4, v17, 3 bitop3:0x6c
	v_lshl_add_u64 v[8:9], v[8:9], 0, s[4:5]
	v_lshlrev_b32_e32 v16, 4, v18
	v_add_u32_e32 v19, s80, v14
	v_add_u32_e32 v106, 0x4000, v14
	v_add_u32_e32 v14, s81, v14
	v_lshl_add_u64 v[10:11], v[10:11], 0, s[4:5]
	v_lshlrev_b32_e32 v20, 4, v4
	v_mad_i64_i32 v[8:9], s[86:87], v13, s84, v[8:9]
	v_and_b32_e32 v4, 0x70, v16
	v_add_u32_e32 v18, 0x4000, v19
	v_readfirstlane_b32 s92, v19
	v_readfirstlane_b32 s78, v14
	v_add_u32_e32 v87, s80, v15
	v_mad_i64_i32 v[14:15], s[86:87], v13, s84, v[10:11]
	v_lshl_add_u64 v[10:11], v[8:9], 0, v[4:5]
	s_mov_b32 vcc_lo, m0
	s_mov_b32 m0, s92
	s_nop 0
	global_load_lds_dwordx4 v[10:11], off
	s_mov_b32 m0, vcc_lo
	v_readfirstlane_b32 s14, v18
	v_lshl_add_u64 v[8:9], v[14:15], 0, v[4:5]
	s_mov_b32 vcc_lo, m0
	s_mov_b32 m0, s14
	s_nop 0
	global_load_lds_dwordx4 v[8:9], off
	s_mov_b32 m0, vcc_lo
	v_add_u32_e32 v19, s81, v106
	s_add_i32 s95, s92, 0x1000
	s_add_i32 s15, s14, 0x1000
	s_add_i32 s96, s14, 0x2000
	s_add_i32 s97, s14, 0x3000
	v_lshl_add_u64 v[14:15], v[10:11], 0, s[6:7]
	s_mov_b32 s14, m0
	s_mov_b32 m0, s95
	s_nop 0
	global_load_lds_dwordx4 v[14:15], off
	s_mov_b32 m0, s14
	v_lshl_add_u32 v86, v6, 7, s80
	v_readfirstlane_b32 s88, v19
	v_lshl_add_u64 v[18:19], v[8:9], 0, s[6:7]
	s_mov_b32 s14, m0
	s_mov_b32 m0, s15
	s_nop 0
	global_load_lds_dwordx4 v[18:19], off
	s_mov_b32 m0, s14
	s_add_i32 s94, s92, 0x2000
	v_add_u32_e32 v13, v86, v20
	v_add_u32_e32 v16, v87, v20
	v_lshl_add_u64 v[20:21], v[10:11], 0, s[8:9]
	s_mov_b32 s14, m0
	s_mov_b32 m0, s94
	s_nop 0
	global_load_lds_dwordx4 v[20:21], off
	s_mov_b32 m0, s14
	v_lshl_add_u64 v[22:23], v[8:9], 0, s[8:9]
	s_mov_b32 s14, m0
	s_mov_b32 m0, s96
	s_nop 0
	global_load_lds_dwordx4 v[22:23], off
	s_mov_b32 m0, s14
	s_add_i32 s93, s92, 0x3000
	v_lshl_add_u64 v[24:25], v[10:11], 0, s[10:11]
	s_mov_b32 s14, m0
	s_mov_b32 m0, s93
	s_nop 0
	global_load_lds_dwordx4 v[24:25], off
	s_mov_b32 m0, s14
	v_lshl_add_u64 v[26:27], v[8:9], 0, s[10:11]
	s_mov_b32 s14, m0
	s_mov_b32 m0, s97
	s_nop 0
	global_load_lds_dwordx4 v[26:27], off
	s_mov_b32 m0, s14
	v_lshl_add_u64 v[28:29], v[10:11], 0, s[12:13]
	s_waitcnt vmcnt(0)
	s_barrier
	s_mov_b32 s14, m0
	s_mov_b32 m0, s78
	s_nop 0
	global_load_lds_dwordx4 v[28:29], off
	s_mov_b32 m0, s14
	v_lshl_add_u64 v[30:31], v[8:9], 0, s[12:13]
	s_mov_b32 s14, m0
	s_mov_b32 m0, s88
	s_nop 0
	global_load_lds_dwordx4 v[30:31], off
	s_mov_b32 m0, s14
	s_add_i32 s87, s78, 0x1000
	v_lshl_add_u64 v[32:33], v[10:11], 0, s[16:17]
	s_mov_b32 s14, m0
	s_mov_b32 m0, s87
	s_nop 0
	global_load_lds_dwordx4 v[32:33], off
	s_mov_b32 m0, s14
	s_add_i32 s91, s88, 0x1000
	v_lshl_add_u64 v[34:35], v[8:9], 0, s[16:17]
	s_mov_b32 s14, m0
	s_mov_b32 m0, s91
	s_nop 0
	global_load_lds_dwordx4 v[34:35], off
	s_mov_b32 m0, s14
	s_add_i32 s86, s78, 0x2000
	v_lshl_add_u64 v[36:37], v[10:11], 0, s[18:19]
	s_mov_b32 s14, m0
	s_mov_b32 m0, s86
	s_nop 0
	global_load_lds_dwordx4 v[36:37], off
	s_mov_b32 m0, s14
	s_add_i32 s90, s88, 0x2000
	v_lshl_add_u64 v[38:39], v[8:9], 0, s[18:19]
	s_mov_b32 s14, m0
	s_mov_b32 m0, s90
	s_nop 0
	global_load_lds_dwordx4 v[38:39], off
	s_mov_b32 m0, s14
	s_add_i32 s79, s78, 0x3000
	v_lshl_add_u64 v[40:41], v[10:11], 0, s[20:21]
	s_mov_b32 s14, m0
	s_mov_b32 m0, s79
	s_nop 0
	global_load_lds_dwordx4 v[40:41], off
	s_mov_b32 m0, s14
	s_add_i32 s89, s88, 0x3000
	v_lshl_add_u64 v[42:43], v[8:9], 0, s[20:21]
	s_mov_b32 s14, m0
	s_mov_b32 m0, s89
	s_nop 0
	global_load_lds_dwordx4 v[42:43], off
	s_mov_b32 m0, s14
	ds_read_b128 v[18:21], v16 offset:16384
	ds_read_b128 v[22:25], v16 offset:18432
	ds_read_b128 v[26:29], v13
	ds_read_b128 v[30:33], v13 offset:2048
	ds_read_b128 v[38:41], v16 offset:20480
	ds_read_b128 v[46:49], v16 offset:22528
	ds_read_b128 v[66:69], v13 offset:4096
	ds_read_b128 v[70:73], v13 offset:6144
	v_bfe_u32 v4, v7, 4, 2
	v_bitop3_b32 v14, v4, v17, 4 bitop3:0x36
	v_lshlrev_b32_e32 v15, 4, v14
	v_add_u32_e32 v14, v86, v15
	v_add_u32_e32 v15, v87, v15
	s_waitcnt lgkmcnt(5)
	v_mfma_f32_16x16x32_bf16 v[34:37], v[18:21], v[26:29], 0
	ds_read_b128 v[86:89], v15 offset:16384
	ds_read_b128 v[90:93], v15 offset:18432
	v_add_u32_e32 v17, s80, v106
	v_lshl_add_u64 v[106:107], v[10:11], 0, s[22:23]
	v_mfma_f32_16x16x32_bf16 v[42:45], v[22:25], v[26:29], 0
	v_readfirstlane_b32 s96, v17
	v_lshl_add_u64 v[108:109], v[8:9], 0, s[22:23]
	v_lshl_add_u64 v[110:111], v[10:11], 0, s[24:25]
	s_waitcnt lgkmcnt(5)
	v_mfma_f32_16x16x32_bf16 v[50:53], v[38:41], v[26:29], 0
	s_add_i32 s97, s96, 0x1000
	v_lshl_add_u64 v[112:113], v[8:9], 0, s[24:25]
	s_add_i32 vcc_lo, s96, 0x2000
	s_waitcnt lgkmcnt(4)
	v_mfma_f32_16x16x32_bf16 v[26:29], v[46:49], v[26:29], 0
	v_lshl_add_u64 v[114:115], v[10:11], 0, s[26:27]
	v_lshl_add_u64 v[116:117], v[8:9], 0, s[26:27]
	v_lshl_add_u64 v[118:119], v[10:11], 0, s[30:31]
	v_mfma_f32_16x16x32_bf16 v[54:57], v[18:21], v[30:33], 0
	s_add_i32 vcc_hi, s96, 0x3000
	v_lshl_add_u64 v[120:121], v[8:9], 0, s[30:31]
	v_and_b32_e32 v7, 64, v7
	v_mfma_f32_16x16x32_bf16 v[58:61], v[22:25], v[30:33], 0
	s_add_i32 s15, s82, s83
	v_mfma_f32_16x16x32_bf16 v[62:65], v[38:41], v[30:33], 0
	v_mfma_f32_16x16x32_bf16 v[30:33], v[46:49], v[30:33], 0
	s_waitcnt lgkmcnt(3)
; #define GLDS_STAGE(st, kt_) do { \
;         _Pragma("unroll") for (int i_ = 0; i_ < FI; ++i_) { \
;             glds16(ap + (size_t)(32 * i_) * lda + (kt_) * 64, l3a + (st) + tid * 16 + i_ * 4096); \
;             glds16(bp + (size_t)(32 * i_) * ldb + (kt_) * 64, l3a + (st) + OPB + tid * 16 + i_ * 4096); } } while (0)
; #define GLDS_STAGE(st, kt_) do { \
;         _Pragma("unroll") for (int i_ = 0; i_ < 4; ++i_) { \
;             glds16(ap + (size_t)(64 * i_) * lda + (kt_) * 64, l3a + (st) + tid * 16 + i_ * 8192); \
;             glds16(bp + (size_t)(64 * i_) * ldb + (kt_) * 64, l3a + (st) + 32768 + tid * 16 + i_ * 8192); } } while (0)
; template <int WT, class Epi>
; DEV void gemm_tile(const bf16_t* __restrict__ A, int lda, const bf16_t* __restrict__ Bt, int ldb, int K, unsigned char* lds, const Epi& epi) {
;     ...
;     for (int kt = 0; kt < nk; ++kt) {
;         if (NSTG == 4 && kt + 2 < nk) { if (FI == 2) asm volatile("s_waitcnt vmcnt(8)" ::: "memory"); else asm volatile("s_waitcnt vmcnt(0)" ::: "memory"); }
;         else asm volatile("s_waitcnt vmcnt(0)" ::: "memory");
;         __syncthreads();
;         if (kt + NSTG - 1 < nk) GLDS_STAGE(nxt, kt + NSTG - 1);
; #pragma unroll
;         for (int kh = 0; kh < 2; ++kh) {
;             bf16x8 af[FI], bfr[FI];
;             const int ch = ((kh * 4 + fq) ^ sw) << 4;
; #pragma unroll
;             for (int i = 0; i < FI; ++i) { af[i] = *(const bf16x8*)(lds + cur + aoff + i * 2048 + ch); bfr[i] = *(const bf16x8*)(lds + cur + boff + i * 2048 + ch); }
; #pragma unroll
;             for (int mi = 0; mi < FI; ++mi)
; #pragma unroll
;                 for (int ni = 0; ni < FI; ++ni) acc[mi][ni] = __builtin_amdgcn_mfma_f32_16x16x32_bf16(bfr[ni], af[mi], acc[mi][ni], 0, 0, 0);
;         }
	v_mfma_f32_16x16x32_bf16 v[74:77], v[18:21], v[66:69], 0
	v_mfma_f32_16x16x32_bf16 v[78:81], v[22:25], v[66:69], 0
	v_mfma_f32_16x16x32_bf16 v[82:85], v[38:41], v[66:69], 0
	v_mfma_f32_16x16x32_bf16 v[66:69], v[46:49], v[66:69], 0
	s_waitcnt lgkmcnt(2)
	v_mfma_f32_16x16x32_bf16 v[18:21], v[18:21], v[70:73], 0
	v_mfma_f32_16x16x32_bf16 v[22:25], v[22:25], v[70:73], 0
	v_mfma_f32_16x16x32_bf16 v[38:41], v[38:41], v[70:73], 0
	v_mfma_f32_16x16x32_bf16 v[46:49], v[46:49], v[70:73], 0
	ds_read_b128 v[70:73], v14
	ds_read_b128 v[94:97], v14 offset:2048
	ds_read_b128 v[98:101], v15 offset:20480
	ds_read_b128 v[102:105], v15 offset:22528
	s_waitcnt lgkmcnt(3)
	v_mfma_f32_16x16x32_bf16 v[34:37], v[86:89], v[70:73], v[34:37]
	v_mfma_f32_16x16x32_bf16 v[42:45], v[90:93], v[70:73], v[42:45]
	s_waitcnt lgkmcnt(1)
	v_mfma_f32_16x16x32_bf16 v[50:53], v[98:101], v[70:73], v[50:53]
	s_waitcnt lgkmcnt(0)
	v_mfma_f32_16x16x32_bf16 v[26:29], v[102:105], v[70:73], v[26:29]
	v_mfma_f32_16x16x32_bf16 v[54:57], v[86:89], v[94:97], v[54:57]
	v_mfma_f32_16x16x32_bf16 v[58:61], v[90:93], v[94:97], v[58:61]
	v_mfma_f32_16x16x32_bf16 v[62:65], v[98:101], v[94:97], v[62:65]
	v_mfma_f32_16x16x32_bf16 v[30:33], v[102:105], v[94:97], v[30:33]
	ds_read_b128 v[70:73], v14 offset:4096
	ds_read_b128 v[94:97], v14 offset:6144
	s_waitcnt vmcnt(0)
	s_waitcnt lgkmcnt(0)
	s_barrier
	s_mov_b32 s14, m0
	s_mov_b32 m0, s92
	s_nop 0
	global_load_lds_dwordx4 v[106:107], off
	s_mov_b32 m0, s14
	v_mfma_f32_16x16x32_bf16 v[74:77], v[86:89], v[70:73], v[74:77]
	s_mov_b32 s14, m0
	s_mov_b32 m0, s96
	s_nop 0
	global_load_lds_dwordx4 v[108:109], off
	s_mov_b32 m0, s14
	v_lshl_add_u64 v[106:107], v[10:11], 0, s[34:35]
	s_mov_b32 s14, m0
	s_mov_b32 m0, s95
	s_nop 0
	global_load_lds_dwordx4 v[110:111], off
	s_mov_b32 m0, s14
	v_mfma_f32_16x16x32_bf16 v[78:81], v[90:93], v[70:73], v[78:81]
	s_mov_b32 s14, m0
	s_mov_b32 m0, s97
	s_nop 0
	global_load_lds_dwordx4 v[112:113], off
	s_mov_b32 m0, s14
	v_lshl_add_u64 v[108:109], v[8:9], 0, s[34:35]
	s_mov_b32 s14, m0
	s_mov_b32 m0, s94
	s_nop 0
	global_load_lds_dwordx4 v[114:115], off
	s_mov_b32 m0, s14
	v_mfma_f32_16x16x32_bf16 v[82:85], v[98:101], v[70:73], v[82:85]
	s_mov_b32 s14, m0
	s_mov_b32 m0, vcc_lo
	s_nop 0
	global_load_lds_dwordx4 v[116:117], off
	s_mov_b32 m0, s14
	v_lshl_add_u64 v[110:111], v[10:11], 0, s[36:37]
	s_mov_b32 s14, m0
	s_mov_b32 m0, s93
	s_nop 0
	global_load_lds_dwordx4 v[118:119], off
	s_mov_b32 m0, s14
	v_mfma_f32_16x16x32_bf16 v[66:69], v[102:105], v[70:73], v[66:69]
	s_mov_b32 s14, m0
	s_mov_b32 m0, vcc_hi
	s_nop 0
	global_load_lds_dwordx4 v[120:121], off
	s_mov_b32 m0, s14
	v_lshl_add_u64 v[112:113], v[8:9], 0, s[36:37]
	v_lshl_add_u64 v[114:115], v[10:11], 0, s[38:39]
	v_mfma_f32_16x16x32_bf16 v[18:21], v[86:89], v[94:97], v[18:21]
	ds_read_b128 v[70:73], v16 offset:49152
	ds_read_b128 v[86:89], v16 offset:51200
	v_lshl_add_u64 v[116:117], v[8:9], 0, s[38:39]
	v_lshl_add_u64 v[118:119], v[10:11], 0, s[40:41]
	v_mfma_f32_16x16x32_bf16 v[22:25], v[90:93], v[94:97], v[22:25]
	v_lshl_add_u64 v[120:121], v[8:9], 0, s[40:41]
	v_mfma_f32_16x16x32_bf16 v[38:41], v[98:101], v[94:97], v[38:41]
	v_mfma_f32_16x16x32_bf16 v[46:49], v[102:105], v[94:97], v[46:49]
	ds_read_b128 v[90:93], v13 offset:32768
	ds_read_b128 v[94:97], v13 offset:34816
	ds_read_b128 v[98:101], v16 offset:53248
	ds_read_b128 v[102:105], v16 offset:55296
	s_waitcnt lgkmcnt(3)
	v_mfma_f32_16x16x32_bf16 v[34:37], v[70:73], v[90:93], v[34:37]
	v_mfma_f32_16x16x32_bf16 v[42:45], v[86:89], v[90:93], v[42:45]
	s_waitcnt lgkmcnt(1)
	v_mfma_f32_16x16x32_bf16 v[50:53], v[98:101], v[90:93], v[50:53]
	s_waitcnt lgkmcnt(0)
	v_mfma_f32_16x16x32_bf16 v[26:29], v[102:105], v[90:93], v[26:29]
	v_mfma_f32_16x16x32_bf16 v[54:57], v[70:73], v[94:97], v[54:57]
	v_mfma_f32_16x16x32_bf16 v[58:61], v[86:89], v[94:97], v[58:61]
	v_mfma_f32_16x16x32_bf16 v[62:65], v[98:101], v[94:97], v[62:65]
	v_mfma_f32_16x16x32_bf16 v[30:33], v[102:105], v[94:97], v[30:33]
	ds_read_b128 v[90:93], v13 offset:36864
	ds_read_b128 v[94:97], v13 offset:38912
	s_waitcnt lgkmcnt(1)
	v_mfma_f32_16x16x32_bf16 v[74:77], v[70:73], v[90:93], v[74:77]
	v_mfma_f32_16x16x32_bf16 v[78:81], v[86:89], v[90:93], v[78:81]
	v_mfma_f32_16x16x32_bf16 v[82:85], v[98:101], v[90:93], v[82:85]
	v_mfma_f32_16x16x32_bf16 v[66:69], v[102:105], v[90:93], v[66:69]
	s_waitcnt lgkmcnt(0)
	v_mfma_f32_16x16x32_bf16 v[18:21], v[70:73], v[94:97], v[18:21]
	v_mfma_f32_16x16x32_bf16 v[22:25], v[86:89], v[94:97], v[22:25]
	ds_read_b128 v[70:73], v15 offset:49152
	ds_read_b128 v[86:89], v15 offset:51200
	v_mfma_f32_16x16x32_bf16 v[38:41], v[98:101], v[94:97], v[38:41]
	v_mfma_f32_16x16x32_bf16 v[46:49], v[102:105], v[94:97], v[46:49]
	ds_read_b128 v[90:93], v14 offset:32768
	ds_read_b128 v[94:97], v14 offset:34816
	ds_read_b128 v[98:101], v15 offset:53248
	ds_read_b128 v[102:105], v15 offset:55296
	s_waitcnt lgkmcnt(3)
	v_mfma_f32_16x16x32_bf16 v[34:37], v[70:73], v[90:93], v[34:37]
	v_mfma_f32_16x16x32_bf16 v[42:45], v[86:89], v[90:93], v[42:45]
	s_waitcnt lgkmcnt(1)
	v_mfma_f32_16x16x32_bf16 v[50:53], v[98:101], v[90:93], v[50:53]
	s_waitcnt lgkmcnt(0)
	v_mfma_f32_16x16x32_bf16 v[26:29], v[102:105], v[90:93], v[26:29]
	v_mfma_f32_16x16x32_bf16 v[54:57], v[70:73], v[94:97], v[54:57]
	v_mfma_f32_16x16x32_bf16 v[58:61], v[86:89], v[94:97], v[58:61]
	v_mfma_f32_16x16x32_bf16 v[62:65], v[98:101], v[94:97], v[62:65]
	v_mfma_f32_16x16x32_bf16 v[30:33], v[102:105], v[94:97], v[30:33]
	ds_read_b128 v[90:93], v14 offset:36864
	ds_read_b128 v[94:97], v14 offset:38912
	s_waitcnt vmcnt(0)
	s_waitcnt lgkmcnt(0)
	s_barrier
; #define GLDS_STAGE(st, kt_) do { \
;         _Pragma("unroll") for (int i_ = 0; i_ < FI; ++i_) { \
;             glds16(ap + (size_t)(32 * i_) * lda + (kt_) * 64, l3a + (st) + tid * 16 + i_ * 4096); \
;             glds16(bp + (size_t)(32 * i_) * ldb + (kt_) * 64, l3a + (st) + OPB + tid * 16 + i_ * 4096); } } while (0)
; #define GLDS_STAGE(st, kt_) do { \
;         _Pragma("unroll") for (int i_ = 0; i_ < 4; ++i_) { \
;             glds16(ap + (size_t)(64 * i_) * lda + (kt_) * 64, l3a + (st) + tid * 16 + i_ * 8192); \
;             glds16(bp + (size_t)(64 * i_) * ldb + (kt_) * 64, l3a + (st) + 32768 + tid * 16 + i_ * 8192); } } while (0)
; template <int WT, class Epi>
; DEV void gemm_tile(const bf16_t* __restrict__ A, int lda, const bf16_t* __restrict__ Bt, int ldb, int K, unsigned char* lds, const Epi& epi) {
;     ...
;     for (int kt = 0; kt < nk; ++kt) {
;         if (NSTG == 4 && kt + 2 < nk) { if (FI == 2) asm volatile("s_waitcnt vmcnt(8)" ::: "memory"); else asm volatile("s_waitcnt vmcnt(0)" ::: "memory"); }
;         else asm volatile("s_waitcnt vmcnt(0)" ::: "memory");
;         __syncthreads();
;         if (kt + NSTG - 1 < nk) GLDS_STAGE(nxt, kt + NSTG - 1);
; #pragma unroll
;         for (int kh = 0; kh < 2; ++kh) {
;             bf16x8 af[FI], bfr[FI];
;             const int ch = ((kh * 4 + fq) ^ sw) << 4;
; #pragma unroll
;             for (int i = 0; i < FI; ++i) { af[i] = *(const bf16x8*)(lds + cur + aoff + i * 2048 + ch); bfr[i] = *(const bf16x8*)(lds + cur + boff + i * 2048 + ch); }
; #pragma unroll
;             for (int mi = 0; mi < FI; ++mi)
; #pragma unroll
;                 for (int ni = 0; ni < FI; ++ni) acc[mi][ni] = __builtin_amdgcn_mfma_f32_16x16x32_bf16(bfr[ni], af[mi], acc[mi][ni], 0, 0, 0);
;         }
	s_mov_b32 s14, m0
	s_mov_b32 m0, s78
	s_nop 0
	global_load_lds_dwordx4 v[106:107], off
	s_mov_b32 m0, s14
	v_mfma_f32_16x16x32_bf16 v[74:77], v[70:73], v[90:93], v[74:77]
	s_mov_b32 s14, m0
	s_mov_b32 m0, s88
	s_nop 0
	global_load_lds_dwordx4 v[108:109], off
	s_mov_b32 m0, s14
	v_lshl_add_u64 v[106:107], v[10:11], 0, s[42:43]
	s_mov_b32 s14, m0
	s_mov_b32 m0, s87
	s_nop 0
	global_load_lds_dwordx4 v[110:111], off
	s_mov_b32 m0, s14
	v_mfma_f32_16x16x32_bf16 v[78:81], v[86:89], v[90:93], v[78:81]
	s_mov_b32 s14, m0
	s_mov_b32 m0, s91
	s_nop 0
	global_load_lds_dwordx4 v[112:113], off
	s_mov_b32 m0, s14
	v_lshl_add_u64 v[108:109], v[8:9], 0, s[42:43]
	s_mov_b32 s14, m0
	s_mov_b32 m0, s86
	s_nop 0
	global_load_lds_dwordx4 v[114:115], off
	s_mov_b32 m0, s14
	v_mfma_f32_16x16x32_bf16 v[82:85], v[98:101], v[90:93], v[82:85]
	s_mov_b32 s14, m0
	s_mov_b32 m0, s90
	s_nop 0
	global_load_lds_dwordx4 v[116:117], off
	s_mov_b32 m0, s14
	v_lshl_add_u64 v[110:111], v[10:11], 0, s[44:45]
	s_mov_b32 s14, m0
	s_mov_b32 m0, s79
	s_nop 0
	global_load_lds_dwordx4 v[118:119], off
	s_mov_b32 m0, s14
	v_mfma_f32_16x16x32_bf16 v[66:69], v[102:105], v[90:93], v[66:69]
	s_mov_b32 s14, m0
	s_mov_b32 m0, s89
	s_nop 0
	global_load_lds_dwordx4 v[120:121], off
	s_mov_b32 m0, s14
	v_lshl_add_u64 v[112:113], v[8:9], 0, s[44:45]
	v_lshl_add_u64 v[114:115], v[10:11], 0, s[46:47]
	v_mfma_f32_16x16x32_bf16 v[18:21], v[70:73], v[94:97], v[18:21]
	v_lshl_add_u64 v[116:117], v[8:9], 0, s[46:47]
	v_lshl_add_u64 v[118:119], v[10:11], 0, s[48:49]
	v_lshl_add_u64 v[120:121], v[8:9], 0, s[48:49]
	v_mfma_f32_16x16x32_bf16 v[22:25], v[86:89], v[94:97], v[22:25]
	ds_read_b128 v[70:73], v16 offset:16384
	ds_read_b128 v[86:89], v16 offset:18432
	v_mfma_f32_16x16x32_bf16 v[38:41], v[98:101], v[94:97], v[38:41]
	v_mfma_f32_16x16x32_bf16 v[46:49], v[102:105], v[94:97], v[46:49]
	ds_read_b128 v[90:93], v13
	ds_read_b128 v[94:97], v13 offset:2048
	ds_read_b128 v[98:101], v16 offset:20480
	ds_read_b128 v[102:105], v16 offset:22528
	s_waitcnt lgkmcnt(3)
	v_mfma_f32_16x16x32_bf16 v[34:37], v[70:73], v[90:93], v[34:37]
	v_mfma_f32_16x16x32_bf16 v[42:45], v[86:89], v[90:93], v[42:45]
	s_waitcnt lgkmcnt(1)
	v_mfma_f32_16x16x32_bf16 v[50:53], v[98:101], v[90:93], v[50:53]
	s_waitcnt lgkmcnt(0)
	v_mfma_f32_16x16x32_bf16 v[26:29], v[102:105], v[90:93], v[26:29]
	v_mfma_f32_16x16x32_bf16 v[54:57], v[70:73], v[94:97], v[54:57]
	v_mfma_f32_16x16x32_bf16 v[58:61], v[86:89], v[94:97], v[58:61]
	v_mfma_f32_16x16x32_bf16 v[62:65], v[98:101], v[94:97], v[62:65]
	v_mfma_f32_16x16x32_bf16 v[30:33], v[102:105], v[94:97], v[30:33]
	ds_read_b128 v[90:93], v13 offset:4096
	ds_read_b128 v[94:97], v13 offset:6144
	s_waitcnt lgkmcnt(1)
	v_mfma_f32_16x16x32_bf16 v[74:77], v[70:73], v[90:93], v[74:77]
	v_mfma_f32_16x16x32_bf16 v[78:81], v[86:89], v[90:93], v[78:81]
	v_mfma_f32_16x16x32_bf16 v[82:85], v[98:101], v[90:93], v[82:85]
	v_mfma_f32_16x16x32_bf16 v[66:69], v[102:105], v[90:93], v[66:69]
	s_waitcnt lgkmcnt(0)
	v_mfma_f32_16x16x32_bf16 v[18:21], v[70:73], v[94:97], v[18:21]
	v_mfma_f32_16x16x32_bf16 v[22:25], v[86:89], v[94:97], v[22:25]
	ds_read_b128 v[70:73], v15 offset:16384
	ds_read_b128 v[86:89], v15 offset:18432
	v_mfma_f32_16x16x32_bf16 v[38:41], v[98:101], v[94:97], v[38:41]
	v_mfma_f32_16x16x32_bf16 v[46:49], v[102:105], v[94:97], v[46:49]
	ds_read_b128 v[90:93], v14
	ds_read_b128 v[94:97], v14 offset:2048
	ds_read_b128 v[98:101], v15 offset:20480
	ds_read_b128 v[102:105], v15 offset:22528
	s_waitcnt lgkmcnt(3)
	v_mfma_f32_16x16x32_bf16 v[34:37], v[70:73], v[90:93], v[34:37]
	v_mfma_f32_16x16x32_bf16 v[42:45], v[86:89], v[90:93], v[42:45]
	s_waitcnt lgkmcnt(1)
	v_mfma_f32_16x16x32_bf16 v[50:53], v[98:101], v[90:93], v[50:53]
	s_waitcnt lgkmcnt(0)
	v_mfma_f32_16x16x32_bf16 v[26:29], v[102:105], v[90:93], v[26:29]
	v_mfma_f32_16x16x32_bf16 v[54:57], v[70:73], v[94:97], v[54:57]
	v_mfma_f32_16x16x32_bf16 v[58:61], v[86:89], v[94:97], v[58:61]
	v_mfma_f32_16x16x32_bf16 v[62:65], v[98:101], v[94:97], v[62:65]
	v_mfma_f32_16x16x32_bf16 v[30:33], v[102:105], v[94:97], v[30:33]
	ds_read_b128 v[90:93], v14 offset:4096
	ds_read_b128 v[94:97], v14 offset:6144
	s_waitcnt vmcnt(0)
	s_waitcnt lgkmcnt(0)
	s_barrier
	s_mov_b32 s14, m0
	s_mov_b32 m0, s92
	s_nop 0
	global_load_lds_dwordx4 v[106:107], off
	s_mov_b32 m0, s14
	v_mfma_f32_16x16x32_bf16 v[74:77], v[70:73], v[90:93], v[74:77]
	s_mov_b32 s14, m0
	s_mov_b32 m0, s96
	s_nop 0
	global_load_lds_dwordx4 v[108:109], off
	s_mov_b32 m0, s14
	v_lshl_add_u64 v[106:107], v[10:11], 0, s[50:51]
	s_mov_b32 s14, m0
	s_mov_b32 m0, s95
	s_nop 0
	global_load_lds_dwordx4 v[110:111], off
	s_mov_b32 m0, s14
	v_mfma_f32_16x16x32_bf16 v[78:81], v[86:89], v[90:93], v[78:81]
	s_mov_b32 s14, m0
	s_mov_b32 m0, s97
	s_nop 0
	global_load_lds_dwordx4 v[112:113], off
	s_mov_b32 m0, s14
	v_lshl_add_u64 v[108:109], v[8:9], 0, s[50:51]
	s_mov_b32 s14, m0
	s_mov_b32 m0, s94
	s_nop 0
	global_load_lds_dwordx4 v[114:115], off
	s_mov_b32 m0, s14
	v_mfma_f32_16x16x32_bf16 v[82:85], v[98:101], v[90:93], v[82:85]
	s_mov_b32 s14, m0
	s_mov_b32 m0, vcc_lo
	s_nop 0
	global_load_lds_dwordx4 v[116:117], off
	s_mov_b32 m0, s14
	v_lshl_add_u64 v[110:111], v[10:11], 0, s[52:53]
	s_mov_b32 s14, m0
	s_mov_b32 m0, s93
	s_nop 0
	global_load_lds_dwordx4 v[118:119], off
	s_mov_b32 m0, s14
	v_mfma_f32_16x16x32_bf16 v[66:69], v[102:105], v[90:93], v[66:69]
	s_mov_b32 s14, m0
	s_mov_b32 m0, vcc_hi
	s_nop 0
	global_load_lds_dwordx4 v[120:121], off
	s_mov_b32 m0, s14
	v_lshl_add_u64 v[112:113], v[8:9], 0, s[52:53]
	v_lshl_add_u64 v[114:115], v[10:11], 0, s[54:55]
	v_mfma_f32_16x16x32_bf16 v[18:21], v[70:73], v[94:97], v[18:21]
	v_lshl_add_u64 v[116:117], v[8:9], 0, s[54:55]
	v_lshl_add_u64 v[118:119], v[10:11], 0, s[56:57]
	v_lshl_add_u64 v[120:121], v[8:9], 0, s[56:57]
	v_mfma_f32_16x16x32_bf16 v[22:25], v[86:89], v[94:97], v[22:25]
	ds_read_b128 v[70:73], v16 offset:49152
	ds_read_b128 v[86:89], v16 offset:51200
	v_mfma_f32_16x16x32_bf16 v[38:41], v[98:101], v[94:97], v[38:41]
	v_mfma_f32_16x16x32_bf16 v[46:49], v[102:105], v[94:97], v[46:49]
	ds_read_b128 v[90:93], v13 offset:32768
	ds_read_b128 v[94:97], v13 offset:34816
	ds_read_b128 v[98:101], v16 offset:53248
	ds_read_b128 v[102:105], v16 offset:55296
	s_waitcnt lgkmcnt(3)
; #define GLDS_STAGE(st, kt_) do { \
;         _Pragma("unroll") for (int i_ = 0; i_ < FI; ++i_) { \
;             glds16(ap + (size_t)(32 * i_) * lda + (kt_) * 64, l3a + (st) + tid * 16 + i_ * 4096); \
;             glds16(bp + (size_t)(32 * i_) * ldb + (kt_) * 64, l3a + (st) + OPB + tid * 16 + i_ * 4096); } } while (0)
; #define GLDS_STAGE(st, kt_) do { \
;         _Pragma("unroll") for (int i_ = 0; i_ < 4; ++i_) { \
;             glds16(ap + (size_t)(64 * i_) * lda + (kt_) * 64, l3a + (st) + tid * 16 + i_ * 8192); \
;             glds16(bp + (size_t)(64 * i_) * ldb + (kt_) * 64, l3a + (st) + 32768 + tid * 16 + i_ * 8192); } } while (0)
; template <int WT, class Epi>
; DEV void gemm_tile(const bf16_t* __restrict__ A, int lda, const bf16_t* __restrict__ Bt, int ldb, int K, unsigned char* lds, const Epi& epi) {
;     ...
;     for (int kt = 0; kt < nk; ++kt) {
;         if (NSTG == 4 && kt + 2 < nk) { if (FI == 2) asm volatile("s_waitcnt vmcnt(8)" ::: "memory"); else asm volatile("s_waitcnt vmcnt(0)" ::: "memory"); }
;         else asm volatile("s_waitcnt vmcnt(0)" ::: "memory");
;         __syncthreads();
;         if (kt + NSTG - 1 < nk) GLDS_STAGE(nxt, kt + NSTG - 1);
; #pragma unroll
;         for (int kh = 0; kh < 2; ++kh) {
;             bf16x8 af[FI], bfr[FI];
;             const int ch = ((kh * 4 + fq) ^ sw) << 4;
; #pragma unroll
;             for (int i = 0; i < FI; ++i) { af[i] = *(const bf16x8*)(lds + cur + aoff + i * 2048 + ch); bfr[i] = *(const bf16x8*)(lds + cur + boff + i * 2048 + ch); }
; #pragma unroll
;             for (int mi = 0; mi < FI; ++mi)
; #pragma unroll
;                 for (int ni = 0; ni < FI; ++ni) acc[mi][ni] = __builtin_amdgcn_mfma_f32_16x16x32_bf16(bfr[ni], af[mi], acc[mi][ni], 0, 0, 0);
;         }
	v_mfma_f32_16x16x32_bf16 v[34:37], v[70:73], v[90:93], v[34:37]
	v_mfma_f32_16x16x32_bf16 v[42:45], v[86:89], v[90:93], v[42:45]
	s_waitcnt lgkmcnt(1)
	v_mfma_f32_16x16x32_bf16 v[50:53], v[98:101], v[90:93], v[50:53]
	s_waitcnt lgkmcnt(0)
	v_mfma_f32_16x16x32_bf16 v[26:29], v[102:105], v[90:93], v[26:29]
	v_mfma_f32_16x16x32_bf16 v[54:57], v[70:73], v[94:97], v[54:57]
	v_mfma_f32_16x16x32_bf16 v[58:61], v[86:89], v[94:97], v[58:61]
	v_mfma_f32_16x16x32_bf16 v[62:65], v[98:101], v[94:97], v[62:65]
	v_mfma_f32_16x16x32_bf16 v[30:33], v[102:105], v[94:97], v[30:33]
	ds_read_b128 v[90:93], v13 offset:36864
	ds_read_b128 v[94:97], v13 offset:38912
	s_waitcnt lgkmcnt(1)
	v_mfma_f32_16x16x32_bf16 v[74:77], v[70:73], v[90:93], v[74:77]
	v_mfma_f32_16x16x32_bf16 v[78:81], v[86:89], v[90:93], v[78:81]
	v_mfma_f32_16x16x32_bf16 v[82:85], v[98:101], v[90:93], v[82:85]
	v_mfma_f32_16x16x32_bf16 v[66:69], v[102:105], v[90:93], v[66:69]
	s_waitcnt lgkmcnt(0)
	v_mfma_f32_16x16x32_bf16 v[18:21], v[70:73], v[94:97], v[18:21]
	v_mfma_f32_16x16x32_bf16 v[22:25], v[86:89], v[94:97], v[22:25]
	ds_read_b128 v[70:73], v15 offset:49152
	ds_read_b128 v[86:89], v15 offset:51200
	v_mfma_f32_16x16x32_bf16 v[38:41], v[98:101], v[94:97], v[38:41]
	v_mfma_f32_16x16x32_bf16 v[46:49], v[102:105], v[94:97], v[46:49]
	ds_read_b128 v[90:93], v14 offset:32768
	ds_read_b128 v[94:97], v14 offset:34816
	ds_read_b128 v[98:101], v15 offset:53248
	ds_read_b128 v[102:105], v15 offset:55296
	s_waitcnt lgkmcnt(3)
	v_mfma_f32_16x16x32_bf16 v[34:37], v[70:73], v[90:93], v[34:37]
	v_mfma_f32_16x16x32_bf16 v[42:45], v[86:89], v[90:93], v[42:45]
	s_waitcnt lgkmcnt(1)
	v_mfma_f32_16x16x32_bf16 v[50:53], v[98:101], v[90:93], v[50:53]
	s_waitcnt lgkmcnt(0)
	v_mfma_f32_16x16x32_bf16 v[26:29], v[102:105], v[90:93], v[26:29]
	v_mfma_f32_16x16x32_bf16 v[54:57], v[70:73], v[94:97], v[54:57]
	v_mfma_f32_16x16x32_bf16 v[58:61], v[86:89], v[94:97], v[58:61]
	v_mfma_f32_16x16x32_bf16 v[62:65], v[98:101], v[94:97], v[62:65]
	v_mfma_f32_16x16x32_bf16 v[30:33], v[102:105], v[94:97], v[30:33]
	ds_read_b128 v[90:93], v14 offset:36864
	ds_read_b128 v[94:97], v14 offset:38912
	s_waitcnt vmcnt(0)
	s_waitcnt lgkmcnt(0)
	s_barrier
	s_mov_b32 s14, m0
	s_mov_b32 m0, s78
	s_nop 0
	global_load_lds_dwordx4 v[106:107], off
	s_mov_b32 m0, s14
	v_mfma_f32_16x16x32_bf16 v[74:77], v[70:73], v[90:93], v[74:77]
	s_mov_b32 s14, m0
	s_mov_b32 m0, s88
	s_nop 0
	global_load_lds_dwordx4 v[108:109], off
	s_mov_b32 m0, s14
	v_lshl_add_u64 v[106:107], v[10:11], 0, s[58:59]
	s_mov_b32 s14, m0
	s_mov_b32 m0, s87
	s_nop 0
	global_load_lds_dwordx4 v[110:111], off
	s_mov_b32 m0, s14
	v_mfma_f32_16x16x32_bf16 v[78:81], v[86:89], v[90:93], v[78:81]
	s_mov_b32 s14, m0
	s_mov_b32 m0, s91
	s_nop 0
	global_load_lds_dwordx4 v[112:113], off
	s_mov_b32 m0, s14
	v_lshl_add_u64 v[108:109], v[8:9], 0, s[58:59]
	s_mov_b32 s14, m0
	s_mov_b32 m0, s86
	s_nop 0
	global_load_lds_dwordx4 v[114:115], off
	s_mov_b32 m0, s14
	v_mfma_f32_16x16x32_bf16 v[82:85], v[98:101], v[90:93], v[82:85]
	s_mov_b32 s14, m0
	s_mov_b32 m0, s90
	s_nop 0
	global_load_lds_dwordx4 v[116:117], off
	s_mov_b32 m0, s14
	v_lshl_add_u64 v[110:111], v[10:11], 0, s[60:61]
	s_mov_b32 s14, m0
	s_mov_b32 m0, s79
	s_nop 0
	global_load_lds_dwordx4 v[118:119], off
	s_mov_b32 m0, s14
	v_mfma_f32_16x16x32_bf16 v[66:69], v[102:105], v[90:93], v[66:69]
	s_mov_b32 s14, m0
	s_mov_b32 m0, s89
	s_nop 0
	global_load_lds_dwordx4 v[120:121], off
	s_mov_b32 m0, s14
	v_lshl_add_u64 v[112:113], v[8:9], 0, s[60:61]
	v_lshl_add_u64 v[114:115], v[10:11], 0, s[62:63]
	v_mfma_f32_16x16x32_bf16 v[18:21], v[70:73], v[94:97], v[18:21]
	v_lshl_add_u64 v[116:117], v[8:9], 0, s[62:63]
	v_lshl_add_u64 v[118:119], v[10:11], 0, s[64:65]
	v_lshl_add_u64 v[120:121], v[8:9], 0, s[64:65]
	v_mfma_f32_16x16x32_bf16 v[22:25], v[86:89], v[94:97], v[22:25]
	ds_read_b128 v[70:73], v16 offset:16384
	ds_read_b128 v[86:89], v16 offset:18432
	v_mfma_f32_16x16x32_bf16 v[38:41], v[98:101], v[94:97], v[38:41]
	v_mfma_f32_16x16x32_bf16 v[46:49], v[102:105], v[94:97], v[46:49]
	ds_read_b128 v[90:93], v13
	ds_read_b128 v[94:97], v13 offset:2048
	ds_read_b128 v[98:101], v16 offset:20480
	ds_read_b128 v[102:105], v16 offset:22528
	s_waitcnt lgkmcnt(3)
	v_mfma_f32_16x16x32_bf16 v[34:37], v[70:73], v[90:93], v[34:37]
	v_mfma_f32_16x16x32_bf16 v[42:45], v[86:89], v[90:93], v[42:45]
	s_waitcnt lgkmcnt(1)
	v_mfma_f32_16x16x32_bf16 v[50:53], v[98:101], v[90:93], v[50:53]
	s_waitcnt lgkmcnt(0)
	v_mfma_f32_16x16x32_bf16 v[26:29], v[102:105], v[90:93], v[26:29]
	v_mfma_f32_16x16x32_bf16 v[54:57], v[70:73], v[94:97], v[54:57]
	v_mfma_f32_16x16x32_bf16 v[58:61], v[86:89], v[94:97], v[58:61]
	v_mfma_f32_16x16x32_bf16 v[62:65], v[98:101], v[94:97], v[62:65]
	v_mfma_f32_16x16x32_bf16 v[30:33], v[102:105], v[94:97], v[30:33]
	ds_read_b128 v[90:93], v13 offset:4096
	ds_read_b128 v[94:97], v13 offset:6144
	s_waitcnt lgkmcnt(1)
	v_mfma_f32_16x16x32_bf16 v[74:77], v[70:73], v[90:93], v[74:77]
	v_mfma_f32_16x16x32_bf16 v[78:81], v[86:89], v[90:93], v[78:81]
	v_mfma_f32_16x16x32_bf16 v[82:85], v[98:101], v[90:93], v[82:85]
	v_mfma_f32_16x16x32_bf16 v[66:69], v[102:105], v[90:93], v[66:69]
	s_waitcnt lgkmcnt(0)
	v_mfma_f32_16x16x32_bf16 v[18:21], v[70:73], v[94:97], v[18:21]
	v_mfma_f32_16x16x32_bf16 v[22:25], v[86:89], v[94:97], v[22:25]
	ds_read_b128 v[70:73], v15 offset:16384
	ds_read_b128 v[86:89], v15 offset:18432
	v_mfma_f32_16x16x32_bf16 v[38:41], v[98:101], v[94:97], v[38:41]
	v_mfma_f32_16x16x32_bf16 v[46:49], v[102:105], v[94:97], v[46:49]
	ds_read_b128 v[90:93], v14
	ds_read_b128 v[94:97], v14 offset:2048
	ds_read_b128 v[98:101], v15 offset:20480
	ds_read_b128 v[102:105], v15 offset:22528
	s_waitcnt lgkmcnt(3)
	v_mfma_f32_16x16x32_bf16 v[34:37], v[70:73], v[90:93], v[34:37]
	v_mfma_f32_16x16x32_bf16 v[42:45], v[86:89], v[90:93], v[42:45]
	s_waitcnt lgkmcnt(1)
	v_mfma_f32_16x16x32_bf16 v[50:53], v[98:101], v[90:93], v[50:53]
	s_waitcnt lgkmcnt(0)
	v_mfma_f32_16x16x32_bf16 v[26:29], v[102:105], v[90:93], v[26:29]
	v_mfma_f32_16x16x32_bf16 v[54:57], v[70:73], v[94:97], v[54:57]
	v_mfma_f32_16x16x32_bf16 v[58:61], v[86:89], v[94:97], v[58:61]
	v_mfma_f32_16x16x32_bf16 v[62:65], v[98:101], v[94:97], v[62:65]
	v_mfma_f32_16x16x32_bf16 v[30:33], v[102:105], v[94:97], v[30:33]
	ds_read_b128 v[90:93], v14 offset:4096
	ds_read_b128 v[94:97], v14 offset:6144
	s_waitcnt vmcnt(0)
	s_waitcnt lgkmcnt(0)
	s_barrier
; #define GLDS_STAGE(st, kt_) do { \
;         _Pragma("unroll") for (int i_ = 0; i_ < FI; ++i_) { \
;             glds16(ap + (size_t)(32 * i_) * lda + (kt_) * 64, l3a + (st) + tid * 16 + i_ * 4096); \
;             glds16(bp + (size_t)(32 * i_) * ldb + (kt_) * 64, l3a + (st) + OPB + tid * 16 + i_ * 4096); } } while (0)
; #define GLDS_STAGE(st, kt_) do { \
;         _Pragma("unroll") for (int i_ = 0; i_ < 4; ++i_) { \
;             glds16(ap + (size_t)(64 * i_) * lda + (kt_) * 64, l3a + (st) + tid * 16 + i_ * 8192); \
;             glds16(bp + (size_t)(64 * i_) * ldb + (kt_) * 64, l3a + (st) + 32768 + tid * 16 + i_ * 8192); } } while (0)
; template <int WT, class Epi>
; DEV void gemm_tile(const bf16_t* __restrict__ A, int lda, const bf16_t* __restrict__ Bt, int ldb, int K, unsigned char* lds, const Epi& epi) {
;     ...
;     for (int kt = 0; kt < nk; ++kt) {
;         if (NSTG == 4 && kt + 2 < nk) { if (FI == 2) asm volatile("s_waitcnt vmcnt(8)" ::: "memory"); else asm volatile("s_waitcnt vmcnt(0)" ::: "memory"); }
;         else asm volatile("s_waitcnt vmcnt(0)" ::: "memory");
;         __syncthreads();
;         if (kt + NSTG - 1 < nk) GLDS_STAGE(nxt, kt + NSTG - 1);
; #pragma unroll
;         for (int kh = 0; kh < 2; ++kh) {
;             bf16x8 af[FI], bfr[FI];
;             const int ch = ((kh * 4 + fq) ^ sw) << 4;
; #pragma unroll
;             for (int i = 0; i < FI; ++i) { af[i] = *(const bf16x8*)(lds + cur + aoff + i * 2048 + ch); bfr[i] = *(const bf16x8*)(lds + cur + boff + i * 2048 + ch); }
; #pragma unroll
;             for (int mi = 0; mi < FI; ++mi)
; #pragma unroll
;                 for (int ni = 0; ni < FI; ++ni) acc[mi][ni] = __builtin_amdgcn_mfma_f32_16x16x32_bf16(bfr[ni], af[mi], acc[mi][ni], 0, 0, 0);
;         }
	s_mov_b32 s14, m0
	s_mov_b32 m0, s92
	s_nop 0
	global_load_lds_dwordx4 v[106:107], off
	s_mov_b32 m0, s14
	v_mfma_f32_16x16x32_bf16 v[74:77], v[70:73], v[90:93], v[74:77]
	s_mov_b32 s14, m0
	s_mov_b32 m0, s96
	s_nop 0
	global_load_lds_dwordx4 v[108:109], off
	s_mov_b32 m0, s14
	v_lshl_add_u64 v[106:107], v[10:11], 0, s[66:67]
	s_mov_b32 s14, m0
	s_mov_b32 m0, s95
	s_nop 0
	global_load_lds_dwordx4 v[110:111], off
	s_mov_b32 m0, s14
	v_mfma_f32_16x16x32_bf16 v[78:81], v[86:89], v[90:93], v[78:81]
	s_mov_b32 s14, m0
	s_mov_b32 m0, s97
	s_nop 0
	global_load_lds_dwordx4 v[112:113], off
	s_mov_b32 m0, s14
	v_lshl_add_u64 v[108:109], v[8:9], 0, s[66:67]
	s_mov_b32 s14, m0
	s_mov_b32 m0, s94
	s_nop 0
	global_load_lds_dwordx4 v[114:115], off
	s_mov_b32 m0, s14
	v_mfma_f32_16x16x32_bf16 v[82:85], v[98:101], v[90:93], v[82:85]
	s_mov_b32 s14, m0
	s_mov_b32 m0, vcc_lo
	s_nop 0
	global_load_lds_dwordx4 v[116:117], off
	s_mov_b32 m0, s14
	v_lshl_add_u64 v[110:111], v[10:11], 0, s[68:69]
	s_mov_b32 s14, m0
	s_mov_b32 m0, s93
	s_nop 0
	global_load_lds_dwordx4 v[118:119], off
	s_mov_b32 m0, s14
	v_mfma_f32_16x16x32_bf16 v[66:69], v[102:105], v[90:93], v[66:69]
	s_mov_b32 s14, m0
	s_mov_b32 m0, vcc_hi
	s_nop 0
	global_load_lds_dwordx4 v[120:121], off
	s_mov_b32 m0, s14
	v_lshl_add_u64 v[112:113], v[8:9], 0, s[68:69]
	v_lshl_add_u64 v[114:115], v[10:11], 0, s[70:71]
	v_mfma_f32_16x16x32_bf16 v[18:21], v[70:73], v[94:97], v[18:21]
	v_lshl_add_u64 v[116:117], v[8:9], 0, s[70:71]
	v_lshl_add_u64 v[118:119], v[10:11], 0, s[72:73]
	v_lshl_add_u64 v[120:121], v[8:9], 0, s[72:73]
	v_mfma_f32_16x16x32_bf16 v[22:25], v[86:89], v[94:97], v[22:25]
	ds_read_b128 v[70:73], v16 offset:49152
	ds_read_b128 v[86:89], v16 offset:51200
	v_mfma_f32_16x16x32_bf16 v[38:41], v[98:101], v[94:97], v[38:41]
	v_mfma_f32_16x16x32_bf16 v[46:49], v[102:105], v[94:97], v[46:49]
	ds_read_b128 v[90:93], v13 offset:32768
	ds_read_b128 v[94:97], v13 offset:34816
	ds_read_b128 v[98:101], v16 offset:53248
	ds_read_b128 v[102:105], v16 offset:55296
	s_waitcnt lgkmcnt(3)
	v_mfma_f32_16x16x32_bf16 v[34:37], v[70:73], v[90:93], v[34:37]
	v_mfma_f32_16x16x32_bf16 v[42:45], v[86:89], v[90:93], v[42:45]
	s_waitcnt lgkmcnt(1)
	v_mfma_f32_16x16x32_bf16 v[50:53], v[98:101], v[90:93], v[50:53]
	s_waitcnt lgkmcnt(0)
	v_mfma_f32_16x16x32_bf16 v[26:29], v[102:105], v[90:93], v[26:29]
	v_mfma_f32_16x16x32_bf16 v[54:57], v[70:73], v[94:97], v[54:57]
	v_mfma_f32_16x16x32_bf16 v[58:61], v[86:89], v[94:97], v[58:61]
	v_mfma_f32_16x16x32_bf16 v[62:65], v[98:101], v[94:97], v[62:65]
	v_mfma_f32_16x16x32_bf16 v[30:33], v[102:105], v[94:97], v[30:33]
	ds_read_b128 v[90:93], v13 offset:36864
	ds_read_b128 v[94:97], v13 offset:38912
	s_waitcnt lgkmcnt(1)
	v_mfma_f32_16x16x32_bf16 v[74:77], v[70:73], v[90:93], v[74:77]
	v_mfma_f32_16x16x32_bf16 v[78:81], v[86:89], v[90:93], v[78:81]
	v_mfma_f32_16x16x32_bf16 v[82:85], v[98:101], v[90:93], v[82:85]
	v_mfma_f32_16x16x32_bf16 v[66:69], v[102:105], v[90:93], v[66:69]
	s_waitcnt lgkmcnt(0)
	v_mfma_f32_16x16x32_bf16 v[18:21], v[70:73], v[94:97], v[18:21]
	v_mfma_f32_16x16x32_bf16 v[22:25], v[86:89], v[94:97], v[22:25]
	ds_read_b128 v[70:73], v15 offset:49152
	ds_read_b128 v[86:89], v15 offset:51200
	v_mfma_f32_16x16x32_bf16 v[38:41], v[98:101], v[94:97], v[38:41]
	v_mfma_f32_16x16x32_bf16 v[46:49], v[102:105], v[94:97], v[46:49]
	ds_read_b128 v[90:93], v14 offset:32768
	ds_read_b128 v[94:97], v14 offset:34816
	ds_read_b128 v[98:101], v15 offset:53248
	ds_read_b128 v[102:105], v15 offset:55296
	s_waitcnt lgkmcnt(3)
	v_mfma_f32_16x16x32_bf16 v[34:37], v[70:73], v[90:93], v[34:37]
	v_mfma_f32_16x16x32_bf16 v[42:45], v[86:89], v[90:93], v[42:45]
	s_waitcnt lgkmcnt(1)
	v_mfma_f32_16x16x32_bf16 v[50:53], v[98:101], v[90:93], v[50:53]
	s_waitcnt lgkmcnt(0)
	v_mfma_f32_16x16x32_bf16 v[26:29], v[102:105], v[90:93], v[26:29]
	v_mfma_f32_16x16x32_bf16 v[54:57], v[70:73], v[94:97], v[54:57]
	v_mfma_f32_16x16x32_bf16 v[58:61], v[86:89], v[94:97], v[58:61]
	v_mfma_f32_16x16x32_bf16 v[62:65], v[98:101], v[94:97], v[62:65]
	v_mfma_f32_16x16x32_bf16 v[30:33], v[102:105], v[94:97], v[30:33]
	ds_read_b128 v[90:93], v14 offset:36864
	ds_read_b128 v[94:97], v14 offset:38912
	s_waitcnt vmcnt(0)
	s_waitcnt lgkmcnt(0)
	s_barrier
; #define GLDS_STAGE(st, kt_) do { \
;         _Pragma("unroll") for (int i_ = 0; i_ < FI; ++i_) { \
;             glds16(ap + (size_t)(32 * i_) * lda + (kt_) * 64, l3a + (st) + tid * 16 + i_ * 4096); \
;             glds16(bp + (size_t)(32 * i_) * ldb + (kt_) * 64, l3a + (st) + OPB + tid * 16 + i_ * 4096); } } while (0)
; #define GLDS_STAGE(st, kt_) do { \
;         _Pragma("unroll") for (int i_ = 0; i_ < 4; ++i_) { \
;             glds16(ap + (size_t)(64 * i_) * lda + (kt_) * 64, l3a + (st) + tid * 16 + i_ * 8192); \
;             glds16(bp + (size_t)(64 * i_) * ldb + (kt_) * 64, l3a + (st) + 32768 + tid * 16 + i_ * 8192); } } while (0)
; #define VLOOP(t, N) for (int t##0_ = 2 * bid, t = min(t##0_ + vb, (N) - 1); t##0_ < (N); t##0_ += VG, t = min(t##0_ + vb, (N) - 1))
; template <int WT, class Epi>
; DEV void gemm_tile(const bf16_t* __restrict__ A, int lda, const bf16_t* __restrict__ Bt, int ldb, int K, unsigned char* lds, const Epi& epi) {
;     ...
;     for (int kt = 0; kt < nk; ++kt) {
;         if (NSTG == 4 && kt + 2 < nk) { if (FI == 2) asm volatile("s_waitcnt vmcnt(8)" ::: "memory"); else asm volatile("s_waitcnt vmcnt(0)" ::: "memory"); }
;         else asm volatile("s_waitcnt vmcnt(0)" ::: "memory");
;         __syncthreads();
;         if (kt + NSTG - 1 < nk) GLDS_STAGE(nxt, kt + NSTG - 1);
; #pragma unroll
;         for (int kh = 0; kh < 2; ++kh) {
;             bf16x8 af[FI], bfr[FI];
;             const int ch = ((kh * 4 + fq) ^ sw) << 4;
; #pragma unroll
;             for (int i = 0; i < FI; ++i) { af[i] = *(const bf16x8*)(lds + cur + aoff + i * 2048 + ch); bfr[i] = *(const bf16x8*)(lds + cur + boff + i * 2048 + ch); }
; #pragma unroll
;             for (int mi = 0; mi < FI; ++mi)
; #pragma unroll
;                 for (int ni = 0; ni < FI; ++ni) acc[mi][ni] = __builtin_amdgcn_mfma_f32_16x16x32_bf16(bfr[ni], af[mi], acc[mi][ni], 0, 0, 0);
;         }
; __global__ void __launch_bounds__(512) hymba_fwd(Params p) {
;     ...
;         VLOOP(t, NS1) { const int bhd = t >> 5, v = t & 31, mt = v >> 1, nt = v & 1, b = bhd >> 2, hd = bhd & 3;
	s_mov_b32 s14, m0
	s_mov_b32 m0, s78
	s_nop 0
	global_load_lds_dwordx4 v[106:107], off
	s_mov_b32 m0, s14
	v_mfma_f32_16x16x32_bf16 v[74:77], v[70:73], v[90:93], v[74:77]
	s_mov_b32 s14, m0
	s_mov_b32 m0, s88
	s_nop 0
	global_load_lds_dwordx4 v[108:109], off
	s_mov_b32 m0, s14
	s_lshl_b32 s78, s77, 2
	s_mov_b32 s14, m0
	s_mov_b32 m0, s87
	s_nop 0
	global_load_lds_dwordx4 v[110:111], off
	s_mov_b32 m0, s14
	v_mfma_f32_16x16x32_bf16 v[78:81], v[86:89], v[90:93], v[78:81]
	s_mov_b32 s14, m0
	s_mov_b32 m0, s91
	s_nop 0
	global_load_lds_dwordx4 v[112:113], off
	s_mov_b32 m0, s14
	s_ashr_i32 s77, s76, 31
	s_mov_b32 s14, m0
	s_mov_b32 m0, s86
	s_nop 0
	global_load_lds_dwordx4 v[114:115], off
	s_mov_b32 m0, s14
	v_mfma_f32_16x16x32_bf16 v[8:11], v[98:101], v[90:93], v[82:85]
	s_mov_b32 s14, m0
	s_mov_b32 m0, s90
	s_nop 0
	global_load_lds_dwordx4 v[116:117], off
	s_mov_b32 m0, s14
	s_lshl_b64 s[76:77], s[76:77], 12
	s_mov_b32 s14, m0
	s_mov_b32 m0, s79
	s_nop 0
	global_load_lds_dwordx4 v[118:119], off
	s_mov_b32 m0, s14
	v_mfma_f32_16x16x32_bf16 v[66:69], v[102:105], v[90:93], v[66:69]
	s_mov_b32 s14, m0
	s_mov_b32 m0, s89
	s_nop 0
	global_load_lds_dwordx4 v[120:121], off
	s_mov_b32 m0, s14
	s_mov_b32 s79, s5
	s_add_i32 s14, s83, s75
	v_mfma_f32_16x16x32_bf16 v[18:21], v[70:73], v[94:97], v[18:21]
	ds_read_b128 v[70:73], v16 offset:16384
	ds_read_b128 v[82:85], v16 offset:18432
	s_min_i32 s86, s15, 0x1ff
	s_mov_b32 s83, s14
	v_mfma_f32_16x16x32_bf16 v[22:25], v[86:89], v[94:97], v[22:25]
	ds_read_b128 v[86:89], v13
	ds_read_b128 v[90:93], v13 offset:2048
	s_cmpk_lt_i32 s14, 0x200
	v_mfma_f32_16x16x32_bf16 v[38:41], v[98:101], v[94:97], v[38:41]
	ds_read_b128 v[98:101], v16 offset:22528
	v_mfma_f32_16x16x32_bf16 v[46:49], v[102:105], v[94:97], v[46:49]
	ds_read_b128 v[94:97], v16 offset:20480
	v_or_b32_e32 v102, 48, v6
	v_lshl_add_u64 v[104:105], v[2:3], 0, s[76:77]
	s_waitcnt lgkmcnt(3)
	v_mfma_f32_16x16x32_bf16 v[34:37], v[70:73], v[86:89], v[34:37]
	v_ashrrev_i32_e32 v103, 31, v102
	v_mfma_f32_16x16x32_bf16 v[42:45], v[82:85], v[86:89], v[42:45]
	s_waitcnt lgkmcnt(0)
	v_mfma_f32_16x16x32_bf16 v[50:53], v[94:97], v[86:89], v[50:53]
	v_mfma_f32_16x16x32_bf16 v[26:29], v[98:101], v[86:89], v[26:29]
	v_mfma_f32_16x16x32_bf16 v[54:57], v[70:73], v[90:93], v[54:57]
	v_mfma_f32_16x16x32_bf16 v[58:61], v[82:85], v[90:93], v[58:61]
	v_mfma_f32_16x16x32_bf16 v[62:65], v[94:97], v[90:93], v[62:65]
	v_mfma_f32_16x16x32_bf16 v[30:33], v[98:101], v[90:93], v[30:33]
	ds_read_b128 v[86:89], v13 offset:4096
	ds_read_b128 v[90:93], v13 offset:6144
	s_waitcnt lgkmcnt(1)
	v_mfma_f32_16x16x32_bf16 v[74:77], v[70:73], v[86:89], v[74:77]
	v_mfma_f32_16x16x32_bf16 v[78:81], v[82:85], v[86:89], v[78:81]
	v_mfma_f32_16x16x32_bf16 v[8:11], v[94:97], v[86:89], v[8:11]
	v_mfma_f32_16x16x32_bf16 v[66:69], v[98:101], v[86:89], v[66:69]
	s_waitcnt lgkmcnt(0)
	v_mfma_f32_16x16x32_bf16 v[18:21], v[70:73], v[90:93], v[18:21]
	v_mfma_f32_16x16x32_bf16 v[22:25], v[82:85], v[90:93], v[22:25]
	ds_read_b128 v[70:73], v15 offset:16384
	ds_read_b128 v[82:85], v15 offset:18432
	v_mfma_f32_16x16x32_bf16 v[38:41], v[94:97], v[90:93], v[38:41]
	v_mfma_f32_16x16x32_bf16 v[46:49], v[98:101], v[90:93], v[46:49]
	ds_read_b128 v[86:89], v14
	ds_read_b128 v[90:93], v14 offset:2048
	ds_read_b128 v[94:97], v15 offset:20480
	ds_read_b128 v[98:101], v15 offset:22528
	s_waitcnt lgkmcnt(3)
	v_mfma_f32_16x16x32_bf16 v[34:37], v[70:73], v[86:89], v[34:37]
	v_mfma_f32_16x16x32_bf16 v[42:45], v[82:85], v[86:89], v[42:45]
	s_waitcnt lgkmcnt(1)
	v_mfma_f32_16x16x32_bf16 v[50:53], v[94:97], v[86:89], v[50:53]
	s_waitcnt lgkmcnt(0)
	v_mfma_f32_16x16x32_bf16 v[26:29], v[98:101], v[86:89], v[26:29]
	v_mfma_f32_16x16x32_bf16 v[54:57], v[70:73], v[90:93], v[54:57]
	v_mfma_f32_16x16x32_bf16 v[58:61], v[82:85], v[90:93], v[58:61]
	v_mfma_f32_16x16x32_bf16 v[62:65], v[94:97], v[90:93], v[62:65]
	v_mfma_f32_16x16x32_bf16 v[30:33], v[98:101], v[90:93], v[30:33]
	ds_read_b128 v[86:89], v14 offset:4096
	ds_read_b128 v[90:93], v14 offset:6144
	s_waitcnt vmcnt(0)
	s_waitcnt lgkmcnt(0)
	v_mfma_f32_16x16x32_bf16 v[74:77], v[70:73], v[86:89], v[74:77]
	s_barrier
	v_mfma_f32_16x16x32_bf16 v[78:81], v[82:85], v[86:89], v[78:81]
	v_mfma_f32_16x16x32_bf16 v[8:11], v[94:97], v[86:89], v[8:11]
	v_mfma_f32_16x16x32_bf16 v[66:69], v[98:101], v[86:89], v[66:69]
	ds_read_b128 v[86:89], v16 offset:51200
	v_mfma_f32_16x16x32_bf16 v[18:21], v[70:73], v[90:93], v[18:21]
	ds_read_b128 v[70:73], v16 offset:49152
	v_mfma_f32_16x16x32_bf16 v[22:25], v[82:85], v[90:93], v[22:25]
	ds_read_b128 v[82:85], v13 offset:32768
	v_mfma_f32_16x16x32_bf16 v[38:41], v[94:97], v[90:93], v[38:41]
	ds_read_b128 v[94:97], v16 offset:55296
	v_mfma_f32_16x16x32_bf16 v[46:49], v[98:101], v[90:93], v[46:49]
	ds_read_b128 v[90:93], v16 offset:53248
	v_or_b32_e32 v98, 16, v6
	v_or_b32_e32 v100, 32, v6
	s_waitcnt lgkmcnt(2)
	v_mfma_f32_16x16x32_bf16 v[34:37], v[70:73], v[82:85], v[34:37]
	v_ashrrev_i32_e32 v99, 31, v98
	v_ashrrev_i32_e32 v101, 31, v100
	v_mfma_f32_16x16x32_bf16 v[42:45], v[86:89], v[82:85], v[42:45]
	s_waitcnt lgkmcnt(0)
	v_mfma_f32_16x16x32_bf16 v[50:53], v[90:93], v[82:85], v[50:53]
	v_mfma_f32_16x16x32_bf16 v[26:29], v[94:97], v[82:85], v[26:29]
	ds_read_b128 v[82:85], v13 offset:34816
	s_waitcnt lgkmcnt(0)
	v_mfma_f32_16x16x32_bf16 v[54:57], v[70:73], v[82:85], v[54:57]
	v_mfma_f32_16x16x32_bf16 v[58:61], v[86:89], v[82:85], v[58:61]
	v_mfma_f32_16x16x32_bf16 v[62:65], v[90:93], v[82:85], v[62:65]
	v_mfma_f32_16x16x32_bf16 v[30:33], v[94:97], v[82:85], v[30:33]
	ds_read_b128 v[82:85], v13 offset:36864
	s_waitcnt lgkmcnt(0)
; template <int WT, class Epi>
; DEV void gemm_tile(const bf16_t* __restrict__ A, int lda, const bf16_t* __restrict__ Bt, int ldb, int K, unsigned char* lds, const Epi& epi) {
;     ...
;         for (int mi = 0; mi < FI; ++mi)
; #pragma unroll
;             for (int ni = 0; ni < FI; ++ni) epi(wr * WT + mi * 16 + fr, wc * WT + ni * 16 + fq * 4, acc[mi][ni]);
	v_mfma_f32_16x16x32_bf16 v[74:77], v[70:73], v[82:85], v[74:77]
	v_mfma_f32_16x16x32_bf16 v[78:81], v[86:89], v[82:85], v[78:81]
	v_mfma_f32_16x16x32_bf16 v[8:11], v[90:93], v[82:85], v[8:11]
	v_mfma_f32_16x16x32_bf16 v[66:69], v[94:97], v[82:85], v[66:69]
	ds_read_b128 v[82:85], v13 offset:38912
	v_lshlrev_b32_e32 v13, 2, v7
	v_ashrrev_i32_e32 v7, 31, v6
	s_waitcnt lgkmcnt(0)
	v_mfma_f32_16x16x32_bf16 v[16:19], v[70:73], v[82:85], v[18:21]
	ds_read_b128 v[70:73], v15 offset:49152
	v_lshlrev_b64 v[106:107], 12, v[6:7]
	v_lshl_add_u64 v[6:7], v[104:105], 0, s[4:5]
	v_mfma_f32_16x16x32_bf16 v[20:23], v[86:89], v[82:85], v[22:25]
	ds_read_b128 v[86:89], v15 offset:51200
	v_lshl_or_b32 v4, v4, 4, v13
	v_mfma_f32_16x16x32_bf16 v[38:41], v[90:93], v[82:85], v[38:41]
	ds_read_b128 v[90:93], v15 offset:53248
	v_mfma_f32_16x16x32_bf16 v[46:49], v[94:97], v[82:85], v[46:49]
	ds_read_b128 v[94:97], v15 offset:55296
	ds_read_b128 v[82:85], v14 offset:32768
	s_waitcnt lgkmcnt(0)
	v_mfma_f32_16x16x32_bf16 v[34:37], v[70:73], v[82:85], v[34:37]
	v_mfma_f32_16x16x32_bf16 v[42:45], v[86:89], v[82:85], v[42:45]
	s_nop 6
	v_mul_f32_e64 v36, v36, s74
	v_mul_f32_e64 v37, v37, s74
	v_pk_mul_f32 v[34:35], v[34:35], s[74:75] op_sel_hi:[1,0]
	v_mfma_f32_16x16x32_bf16 v[50:53], v[90:93], v[82:85], v[50:53]
	v_mfma_f32_16x16x32_bf16 v[24:27], v[94:97], v[82:85], v[26:29]
	ds_read_b128 v[82:85], v14 offset:34816
	v_pk_mul_f32 v[44:45], v[44:45], s[74:75] op_sel_hi:[1,0]
	v_pk_mul_f32 v[42:43], v[42:43], s[74:75] op_sel_hi:[1,0]
	s_waitcnt lgkmcnt(0)
	v_mfma_f32_16x16x32_bf16 v[54:57], v[70:73], v[82:85], v[54:57]
	s_nop 1
	v_mul_f32_e64 v52, v52, s74
	v_mul_f32_e64 v53, v53, s74
	v_pk_mul_f32 v[50:51], v[50:51], s[74:75] op_sel_hi:[1,0]
	v_pk_mul_f32 v[26:27], v[26:27], s[74:75] op_sel_hi:[1,0]
	v_mfma_f32_16x16x32_bf16 v[58:61], v[86:89], v[82:85], v[58:61]
	v_mul_f32_e64 v24, v24, s74
	v_mul_f32_e64 v25, v25, s74
	v_pk_mul_f32 v[56:57], v[56:57], s[74:75] op_sel_hi:[1,0]
	v_pk_mul_f32 v[54:55], v[54:55], s[74:75] op_sel_hi:[1,0]
	v_mfma_f32_16x16x32_bf16 v[62:65], v[90:93], v[82:85], v[62:65]
	v_mfma_f32_16x16x32_bf16 v[28:31], v[94:97], v[82:85], v[30:33]
	ds_read_b128 v[82:85], v14 offset:36864
	s_nop 0
	v_pk_mul_f32 v[60:61], v[60:61], s[74:75] op_sel_hi:[1,0]
	v_pk_mul_f32 v[58:59], v[58:59], s[74:75] op_sel_hi:[1,0]
	s_waitcnt lgkmcnt(0)
	v_mfma_f32_16x16x32_bf16 v[74:77], v[70:73], v[82:85], v[74:77]
	v_lshlrev_b64 v[32:33], 12, v[98:99]
	v_lshlrev_b64 v[98:99], 12, v[100:101]
	v_lshlrev_b64 v[100:101], 12, v[102:103]
	v_mfma_f32_16x16x32_bf16 v[78:81], v[86:89], v[82:85], v[78:81]
	v_lshl_add_u64 v[102:103], v[6:7], 0, s[78:79]
	v_lshl_add_u64 v[32:33], v[102:103], 0, v[32:33]
	v_pk_mul_f32 v[64:65], v[64:65], s[74:75] op_sel_hi:[1,0]
	v_mfma_f32_16x16x32_bf16 v[6:9], v[90:93], v[82:85], v[8:11]
	v_mul_f32_e64 v62, v62, s74
	v_mul_f32_e64 v63, v63, s74
	v_pk_mul_f32 v[30:31], v[30:31], s[74:75] op_sel_hi:[1,0]
	v_pk_mul_f32 v[28:29], v[28:29], s[74:75] op_sel_hi:[1,0]
	v_mfma_f32_16x16x32_bf16 v[66:69], v[94:97], v[82:85], v[66:69]
	ds_read_b128 v[82:85], v14 offset:38912
	v_lshl_add_u64 v[10:11], v[102:103], 0, v[106:107]
	v_lshl_add_u64 v[10:11], v[10:11], 0, v[4:5]
	s_waitcnt lgkmcnt(0)
	v_mfma_f32_16x16x32_bf16 v[14:17], v[70:73], v[82:85], v[16:19]
	v_lshl_add_u64 v[70:71], v[102:103], 0, v[98:99]
	v_lshl_add_u64 v[72:73], v[102:103], 0, v[100:101]
	v_mfma_f32_16x16x32_bf16 v[18:21], v[86:89], v[82:85], v[20:23]
	v_lshl_add_u64 v[86:87], v[72:73], 0, v[4:5]
	s_barrier
	v_mfma_f32_16x16x32_bf16 v[38:41], v[90:93], v[82:85], v[38:41]
	v_lshl_add_u64 v[22:23], v[32:33], 0, v[4:5]
	v_lshl_add_u64 v[32:33], v[70:71], 0, v[4:5]
	v_pk_mul_f32 v[72:73], v[76:77], s[74:75] op_sel_hi:[1,0]
	v_mfma_f32_16x16x32_bf16 v[46:49], v[94:97], v[82:85], v[46:49]
	v_mul_f32_e64 v70, v74, s74
	v_mul_f32_e64 v71, v75, s74
	v_pk_mul_f32 v[76:77], v[80:81], s[74:75] op_sel_hi:[1,0]
	v_pk_mul_f32 v[74:75], v[78:79], s[74:75] op_sel_hi:[1,0]
	v_pk_mul_f32 v[8:9], v[8:9], s[74:75] op_sel_hi:[1,0]
	v_pk_mul_f32 v[6:7], v[6:7], s[74:75] op_sel_hi:[1,0]
	v_pk_mul_f32 v[68:69], v[68:69], s[74:75] op_sel_hi:[1,0]
	v_pk_mul_f32 v[66:67], v[66:67], s[74:75] op_sel_hi:[1,0]
	v_pk_mul_f32 v[16:17], v[16:17], s[74:75] op_sel_hi:[1,0]
	v_pk_mul_f32 v[14:15], v[14:15], s[74:75] op_sel_hi:[1,0]
	v_pk_mul_f32 v[20:21], v[20:21], s[74:75] op_sel_hi:[1,0]
	v_pk_mul_f32 v[18:19], v[18:19], s[74:75] op_sel_hi:[1,0]
	v_pk_mul_f32 v[40:41], v[40:41], s[74:75] op_sel_hi:[1,0]
	v_pk_mul_f32 v[38:39], v[38:39], s[74:75] op_sel_hi:[1,0]
	v_pk_mul_f32 v[48:49], v[48:49], s[74:75] op_sel_hi:[1,0]
	v_pk_mul_f32 v[46:47], v[46:47], s[74:75] op_sel_hi:[1,0]
	global_store_dwordx4 v[10:11], v[34:37], off
	global_store_dwordx4 v[10:11], v[42:45], off offset:64
	global_store_dwordx4 v[10:11], v[50:53], off offset:128
	global_store_dwordx4 v[10:11], v[24:27], off offset:192
	global_store_dwordx4 v[22:23], v[54:57], off
	global_store_dwordx4 v[22:23], v[58:61], off offset:64
	global_store_dwordx4 v[22:23], v[62:65], off offset:128
	global_store_dwordx4 v[22:23], v[28:31], off offset:192
	global_store_dwordx4 v[32:33], v[70:73], off
	global_store_dwordx4 v[32:33], v[74:77], off offset:64
	global_store_dwordx4 v[32:33], v[6:9], off offset:128
	global_store_dwordx4 v[32:33], v[66:69], off offset:192
	global_store_dwordx4 v[86:87], v[14:17], off
	global_store_dwordx4 v[86:87], v[18:21], off offset:64
	global_store_dwordx4 v[86:87], v[38:41], off offset:128
	global_store_dwordx4 v[86:87], v[46:49], off offset:192
	s_cbranch_scc1 .LBB0_1295
	v_readlane_b32 s94, v252, 0
	v_readlane_b32 s95, v252, 1
	s_cmpk_lg_i32 s33, 0x100
	s_cbranch_scc1 .LBB0_1297
; DEV void store_bf4(bf16_t* p, f32x4 v) { uint2 w; w.x = cvt_pk_bf16(v[0], v[1]); w.y = cvt_pk_bf16(v[2], v[3]); *(uint2*)p = w; }
; DEV float wave_max(float v) {
; #pragma unroll
;     for (int o = 32; o >= 1; o >>= 1) v = fmaxf(v, __shfl_xor(v, o));
;     return v;
; }
; __global__ void __launch_bounds__(512) hymba_fwd(Params p) {
;     ...
;     if (IN_PH(9)) { PH_LOCALS
;     for (int r = bid * 8 + wid; r < TP * 4; r += G * 8) {
;         const f32x4 v = __builtin_nontemporal_load((const f32x4*)(sc + (size_t)r * 256 + lane * 4));
;         const float mx = wave_max(fmaxf(fmaxf(v[0], v[1]), fmaxf(v[2], v[3])));
;         f32x4 e; e[0] = __expf(v[0] - mx); e[1] = __expf(v[1] - mx); e[2] = __expf(v[2] - mx); e[3] = __expf(v[3] - mx);
;         const float inv = 1.f / wave_sum(e[0] + e[1] + e[2] + e[3]);
;         store_bf4(pb + (size_t)(r >> 2) * LDP + (r & 3) * 256 + lane * 4, e * inv);
;     }
	s_waitcnt vmcnt(0)
	s_barrier
	v_mbcnt_lo_u32_b32 v2, -1, 0
	v_mbcnt_hi_u32_b32 v2, -1, v2
	v_lshrrev_b32_e32 v6, 6, v0
	s_lshr_b32 s4, s2, 6
	s_lshl_b32 s4, s4, 11
	s_and_b32 s5, s2, 15
	s_lshl_b32 s5, s5, 7
	s_add_i32 s4, s4, s5
	s_bfe_u32 s5, s2, 0x20004
	v_xor_b32_e32 v8, 32, v2
	v_xor_b32_e32 v9, 16, v2
	v_xor_b32_e32 v10, 8, v2
	v_xor_b32_e32 v11, 4, v2
	v_xor_b32_e32 v12, 2, v2
	v_xor_b32_e32 v13, 1, v2
	v_lshlrev_b32_e32 v8, 2, v8
	v_lshlrev_b32_e32 v9, 2, v9
	v_lshlrev_b32_e32 v10, 2, v10
	v_lshlrev_b32_e32 v11, 2, v11
	v_lshlrev_b32_e32 v12, 2, v12
	v_lshlrev_b32_e32 v13, 2, v13
	v_add_u32_e32 v1, s4, v6
	s_lshl_b32 s6, s5, 10
	v_lshlrev_b32_e32 v14, 12, v1
	v_lshl_add_u32 v15, v2, 4, s6
	v_add_u32_e32 v14, v14, v15
	v_mov_b32_e32 v15, 0
	s_mov_b64 s[6:7], 0x1ef39000
	v_lshl_add_u64 v[4:5], v[158:159], 0, s[6:7]
	v_lshl_add_u64 v[4:5], v[4:5], 0, v[14:15]
	s_mov_b64 s[6:7], 0x20f39000
	v_lshl_add_u64 v[20:21], v[158:159], 0, s[6:7]
	s_movk_i32 s12, 0x880
	v_mad_i64_i32 v[20:21], s[16:17], v1, s12, v[20:21]
	s_lshl_b32 s6, s5, 9
	v_lshl_add_u32 v14, v2, 3, s6
	v_lshl_add_u64 v[20:21], v[20:21], 0, v[14:15]
	s_mov_b64 s[8:9], 0x8000
	s_mov_b64 s[10:11], 0x4400
	global_load_dwordx4 v[24:27], v[4:5], off nt
	v_lshl_add_u64 v[4:5], v[4:5], 0, s[8:9]
	global_load_dwordx4 v[28:31], v[4:5], off nt
	v_lshl_add_u64 v[4:5], v[4:5], 0, s[8:9]
	global_load_dwordx4 v[32:35], v[4:5], off nt
	v_lshl_add_u64 v[4:5], v[4:5], 0, s[8:9]
	global_load_dwordx4 v[36:39], v[4:5], off nt
	v_lshl_add_u64 v[4:5], v[4:5], 0, s[8:9]
	global_load_dwordx4 v[40:43], v[4:5], off nt
	v_lshl_add_u64 v[4:5], v[4:5], 0, s[8:9]
	global_load_dwordx4 v[44:47], v[4:5], off nt
	v_lshl_add_u64 v[4:5], v[4:5], 0, s[8:9]
	global_load_dwordx4 v[48:51], v[4:5], off nt
	v_lshl_add_u64 v[4:5], v[4:5], 0, s[8:9]
	global_load_dwordx4 v[52:55], v[4:5], off nt
	v_lshl_add_u64 v[4:5], v[4:5], 0, s[8:9]
	s_waitcnt vmcnt(4)
	v_max_f32_e32 v56, v27, v27
	v_max_f32_e32 v60, v26, v26
	v_max_f32_e32 v56, v60, v56
	v_max3_f32 v56, v24, v25, v56
	v_max_f32_e32 v57, v31, v31
	v_max_f32_e32 v61, v30, v30
	v_max_f32_e32 v57, v61, v57
	v_max3_f32 v57, v28, v29, v57
	v_max_f32_e32 v58, v35, v35
	v_max_f32_e32 v62, v34, v34
	v_max_f32_e32 v58, v62, v58
	v_max3_f32 v58, v32, v33, v58
	v_max_f32_e32 v59, v39, v39
	v_max_f32_e32 v63, v38, v38
	v_max_f32_e32 v59, v63, v59
	v_max3_f32 v59, v36, v37, v59
	ds_bpermute_b32 v60, v8, v56
	ds_bpermute_b32 v61, v8, v57
	ds_bpermute_b32 v62, v8, v58
	ds_bpermute_b32 v63, v8, v59
	s_waitcnt lgkmcnt(3)
	v_max_f32_e32 v60, v60, v60
	v_max_f32_e32 v56, v56, v60
	s_waitcnt lgkmcnt(2)
	v_max_f32_e32 v61, v61, v61
	v_max_f32_e32 v57, v57, v61
	s_waitcnt lgkmcnt(1)
	v_max_f32_e32 v62, v62, v62
	v_max_f32_e32 v58, v58, v62
	s_waitcnt lgkmcnt(0)
	v_max_f32_e32 v63, v63, v63
	v_max_f32_e32 v59, v59, v63
	ds_bpermute_b32 v60, v9, v56
	ds_bpermute_b32 v61, v9, v57
	ds_bpermute_b32 v62, v9, v58
	ds_bpermute_b32 v63, v9, v59
	s_waitcnt lgkmcnt(3)
	v_max_f32_e32 v60, v60, v60
	v_max_f32_e32 v56, v56, v60
	s_waitcnt lgkmcnt(2)
	v_max_f32_e32 v61, v61, v61
	v_max_f32_e32 v57, v57, v61
	s_waitcnt lgkmcnt(1)
	v_max_f32_e32 v62, v62, v62
	v_max_f32_e32 v58, v58, v62
	s_waitcnt lgkmcnt(0)
	v_max_f32_e32 v63, v63, v63
	v_max_f32_e32 v59, v59, v63
	ds_bpermute_b32 v60, v10, v56
	ds_bpermute_b32 v61, v10, v57
	ds_bpermute_b32 v62, v10, v58
	ds_bpermute_b32 v63, v10, v59
	s_waitcnt lgkmcnt(3)
	v_max_f32_e32 v60, v60, v60
	v_max_f32_e32 v56, v56, v60
	s_waitcnt lgkmcnt(2)
	v_max_f32_e32 v61, v61, v61
	v_max_f32_e32 v57, v57, v61
	s_waitcnt lgkmcnt(1)
	v_max_f32_e32 v62, v62, v62
	v_max_f32_e32 v58, v58, v62
	s_waitcnt lgkmcnt(0)
	v_max_f32_e32 v63, v63, v63
	v_max_f32_e32 v59, v59, v63
	ds_bpermute_b32 v60, v11, v56
	ds_bpermute_b32 v61, v11, v57
	ds_bpermute_b32 v62, v11, v58
	ds_bpermute_b32 v63, v11, v59
	s_waitcnt lgkmcnt(3)
	v_max_f32_e32 v60, v60, v60
	v_max_f32_e32 v56, v56, v60
	s_waitcnt lgkmcnt(2)
	v_max_f32_e32 v61, v61, v61
	v_max_f32_e32 v57, v57, v61
	s_waitcnt lgkmcnt(1)
	v_max_f32_e32 v62, v62, v62
	v_max_f32_e32 v58, v58, v62
	s_waitcnt lgkmcnt(0)
	v_max_f32_e32 v63, v63, v63
	v_max_f32_e32 v59, v59, v63
	ds_bpermute_b32 v60, v12, v56
	ds_bpermute_b32 v61, v12, v57
	ds_bpermute_b32 v62, v12, v58
	ds_bpermute_b32 v63, v12, v59
	s_waitcnt lgkmcnt(3)
	v_max_f32_e32 v60, v60, v60
	v_max_f32_e32 v56, v56, v60
	s_waitcnt lgkmcnt(2)
	v_max_f32_e32 v61, v61, v61
	v_max_f32_e32 v57, v57, v61
	s_waitcnt lgkmcnt(1)
	v_max_f32_e32 v62, v62, v62
	v_max_f32_e32 v58, v58, v62
	s_waitcnt lgkmcnt(0)
	v_max_f32_e32 v63, v63, v63
	v_max_f32_e32 v59, v59, v63
	ds_bpermute_b32 v60, v13, v56
	ds_bpermute_b32 v61, v13, v57
	ds_bpermute_b32 v62, v13, v58
	ds_bpermute_b32 v63, v13, v59
	s_waitcnt lgkmcnt(3)
	v_max_f32_e32 v60, v60, v60
	v_max_f32_e32 v56, v56, v60
	s_waitcnt lgkmcnt(2)
	v_max_f32_e32 v61, v61, v61
	v_max_f32_e32 v57, v57, v61
	s_waitcnt lgkmcnt(1)
	v_max_f32_e32 v62, v62, v62
	v_max_f32_e32 v58, v58, v62
	s_waitcnt lgkmcnt(0)
; DEV void store_bf4(bf16_t* p, f32x4 v) { uint2 w; w.x = cvt_pk_bf16(v[0], v[1]); w.y = cvt_pk_bf16(v[2], v[3]); *(uint2*)p = w; }
; DEV float wave_sum(float v) {
; #pragma unroll
;     for (int o = 32; o >= 1; o >>= 1) v += __shfl_xor(v, o);
;     return v;
; }
; __global__ void __launch_bounds__(512) hymba_fwd(Params p) {
;     ...
;         const float mx = wave_max(fmaxf(fmaxf(v[0], v[1]), fmaxf(v[2], v[3])));
;         f32x4 e; e[0] = __expf(v[0] - mx); e[1] = __expf(v[1] - mx); e[2] = __expf(v[2] - mx); e[3] = __expf(v[3] - mx);
;         const float inv = 1.f / wave_sum(e[0] + e[1] + e[2] + e[3]);
;         store_bf4(pb + (size_t)(r >> 2) * LDP + (r & 3) * 256 + lane * 4, e * inv);
	v_max_f32_e32 v63, v63, v63
	v_max_f32_e32 v59, v59, v63
	v_sub_f32_e32 v24, v24, v56
	v_sub_f32_e32 v25, v25, v56
	v_sub_f32_e32 v26, v26, v56
	v_sub_f32_e32 v27, v27, v56
	v_mul_f32_e32 v24, 0x3fb8aa3b, v24
	v_mul_f32_e32 v25, 0x3fb8aa3b, v25
	v_mul_f32_e32 v26, 0x3fb8aa3b, v26
	v_mul_f32_e32 v27, 0x3fb8aa3b, v27
	v_sub_f32_e32 v28, v28, v57
	v_sub_f32_e32 v29, v29, v57
	v_sub_f32_e32 v30, v30, v57
	v_sub_f32_e32 v31, v31, v57
	v_mul_f32_e32 v28, 0x3fb8aa3b, v28
	v_mul_f32_e32 v29, 0x3fb8aa3b, v29
	v_mul_f32_e32 v30, 0x3fb8aa3b, v30
	v_mul_f32_e32 v31, 0x3fb8aa3b, v31
	v_sub_f32_e32 v32, v32, v58
	v_sub_f32_e32 v33, v33, v58
	v_sub_f32_e32 v34, v34, v58
	v_sub_f32_e32 v35, v35, v58
	v_mul_f32_e32 v32, 0x3fb8aa3b, v32
	v_mul_f32_e32 v33, 0x3fb8aa3b, v33
	v_mul_f32_e32 v34, 0x3fb8aa3b, v34
	v_mul_f32_e32 v35, 0x3fb8aa3b, v35
	v_sub_f32_e32 v36, v36, v59
	v_sub_f32_e32 v37, v37, v59
	v_sub_f32_e32 v38, v38, v59
	v_sub_f32_e32 v39, v39, v59
	v_mul_f32_e32 v36, 0x3fb8aa3b, v36
	v_mul_f32_e32 v37, 0x3fb8aa3b, v37
	v_mul_f32_e32 v38, 0x3fb8aa3b, v38
	v_mul_f32_e32 v39, 0x3fb8aa3b, v39
	v_exp_f32_e32 v24, v24
	v_exp_f32_e32 v25, v25
	v_exp_f32_e32 v26, v26
	v_exp_f32_e32 v27, v27
	v_exp_f32_e32 v28, v28
	v_exp_f32_e32 v29, v29
	v_exp_f32_e32 v30, v30
	v_exp_f32_e32 v31, v31
	v_exp_f32_e32 v32, v32
	v_exp_f32_e32 v33, v33
	v_exp_f32_e32 v34, v34
	v_exp_f32_e32 v35, v35
	v_exp_f32_e32 v36, v36
	v_exp_f32_e32 v37, v37
	v_exp_f32_e32 v38, v38
	v_exp_f32_e32 v39, v39
	v_add_f32_e32 v56, v24, v25
	v_add_f32_e32 v56, v26, v56
	v_add_f32_e32 v56, v27, v56
	v_add_f32_e32 v57, v28, v29
	v_add_f32_e32 v57, v30, v57
	v_add_f32_e32 v57, v31, v57
	v_add_f32_e32 v58, v32, v33
	v_add_f32_e32 v58, v34, v58
	v_add_f32_e32 v58, v35, v58
	v_add_f32_e32 v59, v36, v37
	v_add_f32_e32 v59, v38, v59
	v_add_f32_e32 v59, v39, v59
	ds_bpermute_b32 v60, v8, v56
	ds_bpermute_b32 v61, v8, v57
	ds_bpermute_b32 v62, v8, v58
	ds_bpermute_b32 v63, v8, v59
	s_waitcnt lgkmcnt(3)
	v_add_f32_e32 v56, v56, v60
	s_waitcnt lgkmcnt(2)
	v_add_f32_e32 v57, v57, v61
	s_waitcnt lgkmcnt(1)
	v_add_f32_e32 v58, v58, v62
	s_waitcnt lgkmcnt(0)
	v_add_f32_e32 v59, v59, v63
	ds_bpermute_b32 v60, v9, v56
	ds_bpermute_b32 v61, v9, v57
	ds_bpermute_b32 v62, v9, v58
	ds_bpermute_b32 v63, v9, v59
	s_waitcnt lgkmcnt(3)
	v_add_f32_e32 v56, v56, v60
	s_waitcnt lgkmcnt(2)
	v_add_f32_e32 v57, v57, v61
	s_waitcnt lgkmcnt(1)
	v_add_f32_e32 v58, v58, v62
	s_waitcnt lgkmcnt(0)
	v_add_f32_e32 v59, v59, v63
	ds_bpermute_b32 v60, v10, v56
	ds_bpermute_b32 v61, v10, v57
	ds_bpermute_b32 v62, v10, v58
	ds_bpermute_b32 v63, v10, v59
	s_waitcnt lgkmcnt(3)
	v_add_f32_e32 v56, v56, v60
	s_waitcnt lgkmcnt(2)
	v_add_f32_e32 v57, v57, v61
	s_waitcnt lgkmcnt(1)
	v_add_f32_e32 v58, v58, v62
	s_waitcnt lgkmcnt(0)
	v_add_f32_e32 v59, v59, v63
	ds_bpermute_b32 v60, v11, v56
	ds_bpermute_b32 v61, v11, v57
	ds_bpermute_b32 v62, v11, v58
	ds_bpermute_b32 v63, v11, v59
	s_waitcnt lgkmcnt(3)
	v_add_f32_e32 v56, v56, v60
	s_waitcnt lgkmcnt(2)
	v_add_f32_e32 v57, v57, v61
	s_waitcnt lgkmcnt(1)
	v_add_f32_e32 v58, v58, v62
	s_waitcnt lgkmcnt(0)
	v_add_f32_e32 v59, v59, v63
	ds_bpermute_b32 v60, v12, v56
	ds_bpermute_b32 v61, v12, v57
	ds_bpermute_b32 v62, v12, v58
	ds_bpermute_b32 v63, v12, v59
	s_waitcnt lgkmcnt(3)
	v_add_f32_e32 v56, v56, v60
	s_waitcnt lgkmcnt(2)
	v_add_f32_e32 v57, v57, v61
	s_waitcnt lgkmcnt(1)
	v_add_f32_e32 v58, v58, v62
	s_waitcnt lgkmcnt(0)
	v_add_f32_e32 v59, v59, v63
	ds_bpermute_b32 v60, v13, v56
	ds_bpermute_b32 v61, v13, v57
	ds_bpermute_b32 v62, v13, v58
	ds_bpermute_b32 v63, v13, v59
	s_waitcnt lgkmcnt(3)
	v_add_f32_e32 v56, v56, v60
	s_waitcnt lgkmcnt(2)
	v_add_f32_e32 v57, v57, v61
	s_waitcnt lgkmcnt(1)
	v_add_f32_e32 v58, v58, v62
	s_waitcnt lgkmcnt(0)
	v_add_f32_e32 v59, v59, v63
	v_rcp_f32_e32 v64, v56
	s_nop 0
	v_mov_b32_e32 v56, v64
	v_mul_f32_e32 v24, v24, v56
	v_mul_f32_e32 v25, v25, v56
	v_mul_f32_e32 v26, v26, v56
	v_mul_f32_e32 v27, v27, v56
	v_cvt_pk_bf16_f32 v24, v24, v25
	v_cvt_pk_bf16_f32 v25, v26, v27
	global_store_dwordx2 v[20:21], v[24:25], off
	v_lshl_add_u64 v[20:21], v[20:21], 0, s[10:11]
	v_rcp_f32_e32 v64, v57
	s_nop 0
	v_mov_b32_e32 v57, v64
	v_mul_f32_e32 v28, v28, v57
	v_mul_f32_e32 v29, v29, v57
	v_mul_f32_e32 v30, v30, v57
	v_mul_f32_e32 v31, v31, v57
	v_cvt_pk_bf16_f32 v28, v28, v29
	v_cvt_pk_bf16_f32 v29, v30, v31
	global_store_dwordx2 v[20:21], v[28:29], off
	v_lshl_add_u64 v[20:21], v[20:21], 0, s[10:11]
	v_rcp_f32_e32 v64, v58
	s_nop 0
	v_mov_b32_e32 v58, v64
	v_mul_f32_e32 v32, v32, v58
	v_mul_f32_e32 v33, v33, v58
	v_mul_f32_e32 v34, v34, v58
	v_mul_f32_e32 v35, v35, v58
	v_cvt_pk_bf16_f32 v32, v32, v33
	v_cvt_pk_bf16_f32 v33, v34, v35
	global_store_dwordx2 v[20:21], v[32:33], off
	v_lshl_add_u64 v[20:21], v[20:21], 0, s[10:11]
	v_rcp_f32_e32 v64, v59
	s_nop 0
	v_mov_b32_e32 v59, v64
	v_mul_f32_e32 v36, v36, v59
	v_mul_f32_e32 v37, v37, v59
	v_mul_f32_e32 v38, v38, v59
	v_mul_f32_e32 v39, v39, v59
	v_cvt_pk_bf16_f32 v36, v36, v37
	v_cvt_pk_bf16_f32 v37, v38, v39
	global_store_dwordx2 v[20:21], v[36:37], off
	v_lshl_add_u64 v[20:21], v[20:21], 0, s[10:11]
	global_load_dwordx4 v[24:27], v[4:5], off nt
	v_lshl_add_u64 v[4:5], v[4:5], 0, s[8:9]
	global_load_dwordx4 v[28:31], v[4:5], off nt
	v_lshl_add_u64 v[4:5], v[4:5], 0, s[8:9]
	global_load_dwordx4 v[32:35], v[4:5], off nt
	v_lshl_add_u64 v[4:5], v[4:5], 0, s[8:9]
	global_load_dwordx4 v[36:39], v[4:5], off nt
	v_lshl_add_u64 v[4:5], v[4:5], 0, s[8:9]
	s_waitcnt vmcnt(8)
; DEV float wave_sum(float v) {
; #pragma unroll
;     for (int o = 32; o >= 1; o >>= 1) v += __shfl_xor(v, o);
;     return v;
; }
; DEV float wave_max(float v) {
; #pragma unroll
;     for (int o = 32; o >= 1; o >>= 1) v = fmaxf(v, __shfl_xor(v, o));
;     return v;
; }
; __global__ void __launch_bounds__(512) hymba_fwd(Params p) {
;     ...
;         const float mx = wave_max(fmaxf(fmaxf(v[0], v[1]), fmaxf(v[2], v[3])));
;         f32x4 e; e[0] = __expf(v[0] - mx); e[1] = __expf(v[1] - mx); e[2] = __expf(v[2] - mx); e[3] = __expf(v[3] - mx);
;         const float inv = 1.f / wave_sum(e[0] + e[1] + e[2] + e[3]);
	v_max_f32_e32 v56, v43, v43
	v_max_f32_e32 v60, v42, v42
	v_max_f32_e32 v56, v60, v56
	v_max3_f32 v56, v40, v41, v56
	v_max_f32_e32 v57, v47, v47
	v_max_f32_e32 v61, v46, v46
	v_max_f32_e32 v57, v61, v57
	v_max3_f32 v57, v44, v45, v57
	v_max_f32_e32 v58, v51, v51
	v_max_f32_e32 v62, v50, v50
	v_max_f32_e32 v58, v62, v58
	v_max3_f32 v58, v48, v49, v58
	v_max_f32_e32 v59, v55, v55
	v_max_f32_e32 v63, v54, v54
	v_max_f32_e32 v59, v63, v59
	v_max3_f32 v59, v52, v53, v59
	ds_bpermute_b32 v60, v8, v56
	ds_bpermute_b32 v61, v8, v57
	ds_bpermute_b32 v62, v8, v58
	ds_bpermute_b32 v63, v8, v59
	s_waitcnt lgkmcnt(3)
	v_max_f32_e32 v60, v60, v60
	v_max_f32_e32 v56, v56, v60
	s_waitcnt lgkmcnt(2)
	v_max_f32_e32 v61, v61, v61
	v_max_f32_e32 v57, v57, v61
	s_waitcnt lgkmcnt(1)
	v_max_f32_e32 v62, v62, v62
	v_max_f32_e32 v58, v58, v62
	s_waitcnt lgkmcnt(0)
	v_max_f32_e32 v63, v63, v63
	v_max_f32_e32 v59, v59, v63
	ds_bpermute_b32 v60, v9, v56
	ds_bpermute_b32 v61, v9, v57
	ds_bpermute_b32 v62, v9, v58
	ds_bpermute_b32 v63, v9, v59
	s_waitcnt lgkmcnt(3)
	v_max_f32_e32 v60, v60, v60
	v_max_f32_e32 v56, v56, v60
	s_waitcnt lgkmcnt(2)
	v_max_f32_e32 v61, v61, v61
	v_max_f32_e32 v57, v57, v61
	s_waitcnt lgkmcnt(1)
	v_max_f32_e32 v62, v62, v62
	v_max_f32_e32 v58, v58, v62
	s_waitcnt lgkmcnt(0)
	v_max_f32_e32 v63, v63, v63
	v_max_f32_e32 v59, v59, v63
	ds_bpermute_b32 v60, v10, v56
	ds_bpermute_b32 v61, v10, v57
	ds_bpermute_b32 v62, v10, v58
	ds_bpermute_b32 v63, v10, v59
	s_waitcnt lgkmcnt(3)
	v_max_f32_e32 v60, v60, v60
	v_max_f32_e32 v56, v56, v60
	s_waitcnt lgkmcnt(2)
	v_max_f32_e32 v61, v61, v61
	v_max_f32_e32 v57, v57, v61
	s_waitcnt lgkmcnt(1)
	v_max_f32_e32 v62, v62, v62
	v_max_f32_e32 v58, v58, v62
	s_waitcnt lgkmcnt(0)
	v_max_f32_e32 v63, v63, v63
	v_max_f32_e32 v59, v59, v63
	ds_bpermute_b32 v60, v11, v56
	ds_bpermute_b32 v61, v11, v57
	ds_bpermute_b32 v62, v11, v58
	ds_bpermute_b32 v63, v11, v59
	s_waitcnt lgkmcnt(3)
	v_max_f32_e32 v60, v60, v60
	v_max_f32_e32 v56, v56, v60
	s_waitcnt lgkmcnt(2)
	v_max_f32_e32 v61, v61, v61
	v_max_f32_e32 v57, v57, v61
	s_waitcnt lgkmcnt(1)
	v_max_f32_e32 v62, v62, v62
	v_max_f32_e32 v58, v58, v62
	s_waitcnt lgkmcnt(0)
	v_max_f32_e32 v63, v63, v63
	v_max_f32_e32 v59, v59, v63
	ds_bpermute_b32 v60, v12, v56
	ds_bpermute_b32 v61, v12, v57
	ds_bpermute_b32 v62, v12, v58
	ds_bpermute_b32 v63, v12, v59
	s_waitcnt lgkmcnt(3)
	v_max_f32_e32 v60, v60, v60
	v_max_f32_e32 v56, v56, v60
	s_waitcnt lgkmcnt(2)
	v_max_f32_e32 v61, v61, v61
	v_max_f32_e32 v57, v57, v61
	s_waitcnt lgkmcnt(1)
	v_max_f32_e32 v62, v62, v62
	v_max_f32_e32 v58, v58, v62
	s_waitcnt lgkmcnt(0)
	v_max_f32_e32 v63, v63, v63
	v_max_f32_e32 v59, v59, v63
	ds_bpermute_b32 v60, v13, v56
	ds_bpermute_b32 v61, v13, v57
	ds_bpermute_b32 v62, v13, v58
	ds_bpermute_b32 v63, v13, v59
	s_waitcnt lgkmcnt(3)
	v_max_f32_e32 v60, v60, v60
	v_max_f32_e32 v56, v56, v60
	s_waitcnt lgkmcnt(2)
	v_max_f32_e32 v61, v61, v61
	v_max_f32_e32 v57, v57, v61
	s_waitcnt lgkmcnt(1)
	v_max_f32_e32 v62, v62, v62
	v_max_f32_e32 v58, v58, v62
	s_waitcnt lgkmcnt(0)
	v_max_f32_e32 v63, v63, v63
	v_max_f32_e32 v59, v59, v63
	v_sub_f32_e32 v40, v40, v56
	v_sub_f32_e32 v41, v41, v56
	v_sub_f32_e32 v42, v42, v56
	v_sub_f32_e32 v43, v43, v56
	v_mul_f32_e32 v40, 0x3fb8aa3b, v40
	v_mul_f32_e32 v41, 0x3fb8aa3b, v41
	v_mul_f32_e32 v42, 0x3fb8aa3b, v42
	v_mul_f32_e32 v43, 0x3fb8aa3b, v43
	v_sub_f32_e32 v44, v44, v57
	v_sub_f32_e32 v45, v45, v57
	v_sub_f32_e32 v46, v46, v57
	v_sub_f32_e32 v47, v47, v57
	v_mul_f32_e32 v44, 0x3fb8aa3b, v44
	v_mul_f32_e32 v45, 0x3fb8aa3b, v45
	v_mul_f32_e32 v46, 0x3fb8aa3b, v46
	v_mul_f32_e32 v47, 0x3fb8aa3b, v47
	v_sub_f32_e32 v48, v48, v58
	v_sub_f32_e32 v49, v49, v58
	v_sub_f32_e32 v50, v50, v58
	v_sub_f32_e32 v51, v51, v58
	v_mul_f32_e32 v48, 0x3fb8aa3b, v48
	v_mul_f32_e32 v49, 0x3fb8aa3b, v49
	v_mul_f32_e32 v50, 0x3fb8aa3b, v50
	v_mul_f32_e32 v51, 0x3fb8aa3b, v51
	v_sub_f32_e32 v52, v52, v59
	v_sub_f32_e32 v53, v53, v59
	v_sub_f32_e32 v54, v54, v59
	v_sub_f32_e32 v55, v55, v59
	v_mul_f32_e32 v52, 0x3fb8aa3b, v52
	v_mul_f32_e32 v53, 0x3fb8aa3b, v53
	v_mul_f32_e32 v54, 0x3fb8aa3b, v54
	v_mul_f32_e32 v55, 0x3fb8aa3b, v55
	v_exp_f32_e32 v40, v40
	v_exp_f32_e32 v41, v41
	v_exp_f32_e32 v42, v42
	v_exp_f32_e32 v43, v43
	v_exp_f32_e32 v44, v44
	v_exp_f32_e32 v45, v45
	v_exp_f32_e32 v46, v46
	v_exp_f32_e32 v47, v47
	v_exp_f32_e32 v48, v48
	v_exp_f32_e32 v49, v49
	v_exp_f32_e32 v50, v50
	v_exp_f32_e32 v51, v51
	v_exp_f32_e32 v52, v52
	v_exp_f32_e32 v53, v53
	v_exp_f32_e32 v54, v54
	v_exp_f32_e32 v55, v55
	v_add_f32_e32 v56, v40, v41
	v_add_f32_e32 v56, v42, v56
	v_add_f32_e32 v56, v43, v56
	v_add_f32_e32 v57, v44, v45
	v_add_f32_e32 v57, v46, v57
	v_add_f32_e32 v57, v47, v57
	v_add_f32_e32 v58, v48, v49
	v_add_f32_e32 v58, v50, v58
	v_add_f32_e32 v58, v51, v58
	v_add_f32_e32 v59, v52, v53
	v_add_f32_e32 v59, v54, v59
	v_add_f32_e32 v59, v55, v59
	ds_bpermute_b32 v60, v8, v56
	ds_bpermute_b32 v61, v8, v57
	ds_bpermute_b32 v62, v8, v58
	ds_bpermute_b32 v63, v8, v59
	s_waitcnt lgkmcnt(3)
	v_add_f32_e32 v56, v56, v60
	s_waitcnt lgkmcnt(2)
	v_add_f32_e32 v57, v57, v61
	s_waitcnt lgkmcnt(1)
	v_add_f32_e32 v58, v58, v62
	s_waitcnt lgkmcnt(0)
	v_add_f32_e32 v59, v59, v63
	ds_bpermute_b32 v60, v9, v56
	ds_bpermute_b32 v61, v9, v57
	ds_bpermute_b32 v62, v9, v58
	ds_bpermute_b32 v63, v9, v59
	s_waitcnt lgkmcnt(3)
	v_add_f32_e32 v56, v56, v60
	s_waitcnt lgkmcnt(2)
	v_add_f32_e32 v57, v57, v61
	s_waitcnt lgkmcnt(1)
	v_add_f32_e32 v58, v58, v62
	s_waitcnt lgkmcnt(0)
	v_add_f32_e32 v59, v59, v63
	ds_bpermute_b32 v60, v10, v56
	ds_bpermute_b32 v61, v10, v57
	ds_bpermute_b32 v62, v10, v58
	ds_bpermute_b32 v63, v10, v59
	s_waitcnt lgkmcnt(3)
; DEV void store_bf4(bf16_t* p, f32x4 v) { uint2 w; w.x = cvt_pk_bf16(v[0], v[1]); w.y = cvt_pk_bf16(v[2], v[3]); *(uint2*)p = w; }
; DEV float wave_sum(float v) {
; #pragma unroll
;     for (int o = 32; o >= 1; o >>= 1) v += __shfl_xor(v, o);
;     return v;
; }
; __global__ void __launch_bounds__(512) hymba_fwd(Params p) {
;     ...
;         const float inv = 1.f / wave_sum(e[0] + e[1] + e[2] + e[3]);
;         store_bf4(pb + (size_t)(r >> 2) * LDP + (r & 3) * 256 + lane * 4, e * inv);
	v_add_f32_e32 v56, v56, v60
	s_waitcnt lgkmcnt(2)
	v_add_f32_e32 v57, v57, v61
	s_waitcnt lgkmcnt(1)
	v_add_f32_e32 v58, v58, v62
	s_waitcnt lgkmcnt(0)
	v_add_f32_e32 v59, v59, v63
	ds_bpermute_b32 v60, v11, v56
	ds_bpermute_b32 v61, v11, v57
	ds_bpermute_b32 v62, v11, v58
	ds_bpermute_b32 v63, v11, v59
	s_waitcnt lgkmcnt(3)
	v_add_f32_e32 v56, v56, v60
	s_waitcnt lgkmcnt(2)
	v_add_f32_e32 v57, v57, v61
	s_waitcnt lgkmcnt(1)
	v_add_f32_e32 v58, v58, v62
	s_waitcnt lgkmcnt(0)
	v_add_f32_e32 v59, v59, v63
	ds_bpermute_b32 v60, v12, v56
	ds_bpermute_b32 v61, v12, v57
	ds_bpermute_b32 v62, v12, v58
	ds_bpermute_b32 v63, v12, v59
	s_waitcnt lgkmcnt(3)
	v_add_f32_e32 v56, v56, v60
	s_waitcnt lgkmcnt(2)
	v_add_f32_e32 v57, v57, v61
	s_waitcnt lgkmcnt(1)
	v_add_f32_e32 v58, v58, v62
	s_waitcnt lgkmcnt(0)
	v_add_f32_e32 v59, v59, v63
	ds_bpermute_b32 v60, v13, v56
	ds_bpermute_b32 v61, v13, v57
	ds_bpermute_b32 v62, v13, v58
	ds_bpermute_b32 v63, v13, v59
	s_waitcnt lgkmcnt(3)
	v_add_f32_e32 v56, v56, v60
	s_waitcnt lgkmcnt(2)
	v_add_f32_e32 v57, v57, v61
	s_waitcnt lgkmcnt(1)
	v_add_f32_e32 v58, v58, v62
	s_waitcnt lgkmcnt(0)
	v_add_f32_e32 v59, v59, v63
	v_rcp_f32_e32 v64, v56
	s_nop 0
	v_mov_b32_e32 v56, v64
	v_mul_f32_e32 v40, v40, v56
	v_mul_f32_e32 v41, v41, v56
	v_mul_f32_e32 v42, v42, v56
	v_mul_f32_e32 v43, v43, v56
	v_cvt_pk_bf16_f32 v40, v40, v41
	v_cvt_pk_bf16_f32 v41, v42, v43
	global_store_dwordx2 v[20:21], v[40:41], off
	v_lshl_add_u64 v[20:21], v[20:21], 0, s[10:11]
	v_rcp_f32_e32 v64, v57
	s_nop 0
	v_mov_b32_e32 v57, v64
	v_mul_f32_e32 v44, v44, v57
	v_mul_f32_e32 v45, v45, v57
	v_mul_f32_e32 v46, v46, v57
	v_mul_f32_e32 v47, v47, v57
	v_cvt_pk_bf16_f32 v44, v44, v45
	v_cvt_pk_bf16_f32 v45, v46, v47
	global_store_dwordx2 v[20:21], v[44:45], off
	v_lshl_add_u64 v[20:21], v[20:21], 0, s[10:11]
	v_rcp_f32_e32 v64, v58
	s_nop 0
	v_mov_b32_e32 v58, v64
	v_mul_f32_e32 v48, v48, v58
	v_mul_f32_e32 v49, v49, v58
	v_mul_f32_e32 v50, v50, v58
	v_mul_f32_e32 v51, v51, v58
	v_cvt_pk_bf16_f32 v48, v48, v49
	v_cvt_pk_bf16_f32 v49, v50, v51
	global_store_dwordx2 v[20:21], v[48:49], off
	v_lshl_add_u64 v[20:21], v[20:21], 0, s[10:11]
	v_rcp_f32_e32 v64, v59
	s_nop 0
	v_mov_b32_e32 v59, v64
	v_mul_f32_e32 v52, v52, v59
	v_mul_f32_e32 v53, v53, v59
	v_mul_f32_e32 v54, v54, v59
	v_mul_f32_e32 v55, v55, v59
	v_cvt_pk_bf16_f32 v52, v52, v53
	v_cvt_pk_bf16_f32 v53, v54, v55
	global_store_dwordx2 v[20:21], v[52:53], off
	v_lshl_add_u64 v[20:21], v[20:21], 0, s[10:11]
	global_load_dwordx4 v[40:43], v[4:5], off nt
	v_lshl_add_u64 v[4:5], v[4:5], 0, s[8:9]
	global_load_dwordx4 v[44:47], v[4:5], off nt
	v_lshl_add_u64 v[4:5], v[4:5], 0, s[8:9]
	global_load_dwordx4 v[48:51], v[4:5], off nt
	v_lshl_add_u64 v[4:5], v[4:5], 0, s[8:9]
	global_load_dwordx4 v[52:55], v[4:5], off nt
	v_lshl_add_u64 v[4:5], v[4:5], 0, s[8:9]
	s_waitcnt vmcnt(8)
	v_max_f32_e32 v56, v27, v27
	v_max_f32_e32 v60, v26, v26
	v_max_f32_e32 v56, v60, v56
	v_max3_f32 v56, v24, v25, v56
	v_max_f32_e32 v57, v31, v31
	v_max_f32_e32 v61, v30, v30
	v_max_f32_e32 v57, v61, v57
	v_max3_f32 v57, v28, v29, v57
	v_max_f32_e32 v58, v35, v35
	v_max_f32_e32 v62, v34, v34
	v_max_f32_e32 v58, v62, v58
	v_max3_f32 v58, v32, v33, v58
	v_max_f32_e32 v59, v39, v39
	v_max_f32_e32 v63, v38, v38
	v_max_f32_e32 v59, v63, v59
	v_max3_f32 v59, v36, v37, v59
	ds_bpermute_b32 v60, v8, v56
	ds_bpermute_b32 v61, v8, v57
	ds_bpermute_b32 v62, v8, v58
	ds_bpermute_b32 v63, v8, v59
	s_waitcnt lgkmcnt(3)
	v_max_f32_e32 v60, v60, v60
	v_max_f32_e32 v56, v56, v60
	s_waitcnt lgkmcnt(2)
	v_max_f32_e32 v61, v61, v61
	v_max_f32_e32 v57, v57, v61
	s_waitcnt lgkmcnt(1)
	v_max_f32_e32 v62, v62, v62
	v_max_f32_e32 v58, v58, v62
	s_waitcnt lgkmcnt(0)
	v_max_f32_e32 v63, v63, v63
	v_max_f32_e32 v59, v59, v63
	ds_bpermute_b32 v60, v9, v56
	ds_bpermute_b32 v61, v9, v57
	ds_bpermute_b32 v62, v9, v58
	ds_bpermute_b32 v63, v9, v59
	s_waitcnt lgkmcnt(3)
	v_max_f32_e32 v60, v60, v60
	v_max_f32_e32 v56, v56, v60
	s_waitcnt lgkmcnt(2)
	v_max_f32_e32 v61, v61, v61
	v_max_f32_e32 v57, v57, v61
	s_waitcnt lgkmcnt(1)
	v_max_f32_e32 v62, v62, v62
	v_max_f32_e32 v58, v58, v62
	s_waitcnt lgkmcnt(0)
	v_max_f32_e32 v63, v63, v63
	v_max_f32_e32 v59, v59, v63
	ds_bpermute_b32 v60, v10, v56
	ds_bpermute_b32 v61, v10, v57
	ds_bpermute_b32 v62, v10, v58
	ds_bpermute_b32 v63, v10, v59
	s_waitcnt lgkmcnt(3)
	v_max_f32_e32 v60, v60, v60
	v_max_f32_e32 v56, v56, v60
	s_waitcnt lgkmcnt(2)
	v_max_f32_e32 v61, v61, v61
	v_max_f32_e32 v57, v57, v61
	s_waitcnt lgkmcnt(1)
	v_max_f32_e32 v62, v62, v62
	v_max_f32_e32 v58, v58, v62
	s_waitcnt lgkmcnt(0)
	v_max_f32_e32 v63, v63, v63
	v_max_f32_e32 v59, v59, v63
	ds_bpermute_b32 v60, v11, v56
	ds_bpermute_b32 v61, v11, v57
	ds_bpermute_b32 v62, v11, v58
	ds_bpermute_b32 v63, v11, v59
	s_waitcnt lgkmcnt(3)
	v_max_f32_e32 v60, v60, v60
	v_max_f32_e32 v56, v56, v60
	s_waitcnt lgkmcnt(2)
	v_max_f32_e32 v61, v61, v61
	v_max_f32_e32 v57, v57, v61
	s_waitcnt lgkmcnt(1)
	v_max_f32_e32 v62, v62, v62
	v_max_f32_e32 v58, v58, v62
	s_waitcnt lgkmcnt(0)
	v_max_f32_e32 v63, v63, v63
	v_max_f32_e32 v59, v59, v63
	ds_bpermute_b32 v60, v12, v56
	ds_bpermute_b32 v61, v12, v57
	ds_bpermute_b32 v62, v12, v58
	ds_bpermute_b32 v63, v12, v59
	s_waitcnt lgkmcnt(3)
	v_max_f32_e32 v60, v60, v60
	v_max_f32_e32 v56, v56, v60
	s_waitcnt lgkmcnt(2)
	v_max_f32_e32 v61, v61, v61
	v_max_f32_e32 v57, v57, v61
	s_waitcnt lgkmcnt(1)
	v_max_f32_e32 v62, v62, v62
	v_max_f32_e32 v58, v58, v62
	s_waitcnt lgkmcnt(0)
	v_max_f32_e32 v63, v63, v63
	v_max_f32_e32 v59, v59, v63
	ds_bpermute_b32 v60, v13, v56
	ds_bpermute_b32 v61, v13, v57
	ds_bpermute_b32 v62, v13, v58
	ds_bpermute_b32 v63, v13, v59
	s_waitcnt lgkmcnt(3)
; DEV void store_bf4(bf16_t* p, f32x4 v) { uint2 w; w.x = cvt_pk_bf16(v[0], v[1]); w.y = cvt_pk_bf16(v[2], v[3]); *(uint2*)p = w; }
; DEV float wave_sum(float v) {
; #pragma unroll
;     for (int o = 32; o >= 1; o >>= 1) v += __shfl_xor(v, o);
;     return v;
; }
; DEV float wave_max(float v) {
; #pragma unroll
;     for (int o = 32; o >= 1; o >>= 1) v = fmaxf(v, __shfl_xor(v, o));
;     return v;
; }
; __global__ void __launch_bounds__(512) hymba_fwd(Params p) {
;     ...
;         const float mx = wave_max(fmaxf(fmaxf(v[0], v[1]), fmaxf(v[2], v[3])));
;         f32x4 e; e[0] = __expf(v[0] - mx); e[1] = __expf(v[1] - mx); e[2] = __expf(v[2] - mx); e[3] = __expf(v[3] - mx);
;         const float inv = 1.f / wave_sum(e[0] + e[1] + e[2] + e[3]);
;         store_bf4(pb + (size_t)(r >> 2) * LDP + (r & 3) * 256 + lane * 4, e * inv);
	v_max_f32_e32 v60, v60, v60
	v_max_f32_e32 v56, v56, v60
	s_waitcnt lgkmcnt(2)
	v_max_f32_e32 v61, v61, v61
	v_max_f32_e32 v57, v57, v61
	s_waitcnt lgkmcnt(1)
	v_max_f32_e32 v62, v62, v62
	v_max_f32_e32 v58, v58, v62
	s_waitcnt lgkmcnt(0)
	v_max_f32_e32 v63, v63, v63
	v_max_f32_e32 v59, v59, v63
	v_sub_f32_e32 v24, v24, v56
	v_sub_f32_e32 v25, v25, v56
	v_sub_f32_e32 v26, v26, v56
	v_sub_f32_e32 v27, v27, v56
	v_mul_f32_e32 v24, 0x3fb8aa3b, v24
	v_mul_f32_e32 v25, 0x3fb8aa3b, v25
	v_mul_f32_e32 v26, 0x3fb8aa3b, v26
	v_mul_f32_e32 v27, 0x3fb8aa3b, v27
	v_sub_f32_e32 v28, v28, v57
	v_sub_f32_e32 v29, v29, v57
	v_sub_f32_e32 v30, v30, v57
	v_sub_f32_e32 v31, v31, v57
	v_mul_f32_e32 v28, 0x3fb8aa3b, v28
	v_mul_f32_e32 v29, 0x3fb8aa3b, v29
	v_mul_f32_e32 v30, 0x3fb8aa3b, v30
	v_mul_f32_e32 v31, 0x3fb8aa3b, v31
	v_sub_f32_e32 v32, v32, v58
	v_sub_f32_e32 v33, v33, v58
	v_sub_f32_e32 v34, v34, v58
	v_sub_f32_e32 v35, v35, v58
	v_mul_f32_e32 v32, 0x3fb8aa3b, v32
	v_mul_f32_e32 v33, 0x3fb8aa3b, v33
	v_mul_f32_e32 v34, 0x3fb8aa3b, v34
	v_mul_f32_e32 v35, 0x3fb8aa3b, v35
	v_sub_f32_e32 v36, v36, v59
	v_sub_f32_e32 v37, v37, v59
	v_sub_f32_e32 v38, v38, v59
	v_sub_f32_e32 v39, v39, v59
	v_mul_f32_e32 v36, 0x3fb8aa3b, v36
	v_mul_f32_e32 v37, 0x3fb8aa3b, v37
	v_mul_f32_e32 v38, 0x3fb8aa3b, v38
	v_mul_f32_e32 v39, 0x3fb8aa3b, v39
	v_exp_f32_e32 v24, v24
	v_exp_f32_e32 v25, v25
	v_exp_f32_e32 v26, v26
	v_exp_f32_e32 v27, v27
	v_exp_f32_e32 v28, v28
	v_exp_f32_e32 v29, v29
	v_exp_f32_e32 v30, v30
	v_exp_f32_e32 v31, v31
	v_exp_f32_e32 v32, v32
	v_exp_f32_e32 v33, v33
	v_exp_f32_e32 v34, v34
	v_exp_f32_e32 v35, v35
	v_exp_f32_e32 v36, v36
	v_exp_f32_e32 v37, v37
	v_exp_f32_e32 v38, v38
	v_exp_f32_e32 v39, v39
	v_add_f32_e32 v56, v24, v25
	v_add_f32_e32 v56, v26, v56
	v_add_f32_e32 v56, v27, v56
	v_add_f32_e32 v57, v28, v29
	v_add_f32_e32 v57, v30, v57
	v_add_f32_e32 v57, v31, v57
	v_add_f32_e32 v58, v32, v33
	v_add_f32_e32 v58, v34, v58
	v_add_f32_e32 v58, v35, v58
	v_add_f32_e32 v59, v36, v37
	v_add_f32_e32 v59, v38, v59
	v_add_f32_e32 v59, v39, v59
	ds_bpermute_b32 v60, v8, v56
	ds_bpermute_b32 v61, v8, v57
	ds_bpermute_b32 v62, v8, v58
	ds_bpermute_b32 v63, v8, v59
	s_waitcnt lgkmcnt(3)
	v_add_f32_e32 v56, v56, v60
	s_waitcnt lgkmcnt(2)
	v_add_f32_e32 v57, v57, v61
	s_waitcnt lgkmcnt(1)
	v_add_f32_e32 v58, v58, v62
	s_waitcnt lgkmcnt(0)
	v_add_f32_e32 v59, v59, v63
	ds_bpermute_b32 v60, v9, v56
	ds_bpermute_b32 v61, v9, v57
	ds_bpermute_b32 v62, v9, v58
	ds_bpermute_b32 v63, v9, v59
	s_waitcnt lgkmcnt(3)
	v_add_f32_e32 v56, v56, v60
	s_waitcnt lgkmcnt(2)
	v_add_f32_e32 v57, v57, v61
	s_waitcnt lgkmcnt(1)
	v_add_f32_e32 v58, v58, v62
	s_waitcnt lgkmcnt(0)
	v_add_f32_e32 v59, v59, v63
	ds_bpermute_b32 v60, v10, v56
	ds_bpermute_b32 v61, v10, v57
	ds_bpermute_b32 v62, v10, v58
	ds_bpermute_b32 v63, v10, v59
	s_waitcnt lgkmcnt(3)
	v_add_f32_e32 v56, v56, v60
	s_waitcnt lgkmcnt(2)
	v_add_f32_e32 v57, v57, v61
	s_waitcnt lgkmcnt(1)
	v_add_f32_e32 v58, v58, v62
	s_waitcnt lgkmcnt(0)
	v_add_f32_e32 v59, v59, v63
	ds_bpermute_b32 v60, v11, v56
	ds_bpermute_b32 v61, v11, v57
	ds_bpermute_b32 v62, v11, v58
	ds_bpermute_b32 v63, v11, v59
	s_waitcnt lgkmcnt(3)
	v_add_f32_e32 v56, v56, v60
	s_waitcnt lgkmcnt(2)
	v_add_f32_e32 v57, v57, v61
	s_waitcnt lgkmcnt(1)
	v_add_f32_e32 v58, v58, v62
	s_waitcnt lgkmcnt(0)
	v_add_f32_e32 v59, v59, v63
	ds_bpermute_b32 v60, v12, v56
	ds_bpermute_b32 v61, v12, v57
	ds_bpermute_b32 v62, v12, v58
	ds_bpermute_b32 v63, v12, v59
	s_waitcnt lgkmcnt(3)
	v_add_f32_e32 v56, v56, v60
	s_waitcnt lgkmcnt(2)
	v_add_f32_e32 v57, v57, v61
	s_waitcnt lgkmcnt(1)
	v_add_f32_e32 v58, v58, v62
	s_waitcnt lgkmcnt(0)
	v_add_f32_e32 v59, v59, v63
	ds_bpermute_b32 v60, v13, v56
	ds_bpermute_b32 v61, v13, v57
	ds_bpermute_b32 v62, v13, v58
	ds_bpermute_b32 v63, v13, v59
	s_waitcnt lgkmcnt(3)
	v_add_f32_e32 v56, v56, v60
	s_waitcnt lgkmcnt(2)
	v_add_f32_e32 v57, v57, v61
	s_waitcnt lgkmcnt(1)
	v_add_f32_e32 v58, v58, v62
	s_waitcnt lgkmcnt(0)
	v_add_f32_e32 v59, v59, v63
	v_rcp_f32_e32 v64, v56
	s_nop 0
	v_mov_b32_e32 v56, v64
	v_mul_f32_e32 v24, v24, v56
	v_mul_f32_e32 v25, v25, v56
	v_mul_f32_e32 v26, v26, v56
	v_mul_f32_e32 v27, v27, v56
	v_cvt_pk_bf16_f32 v24, v24, v25
	v_cvt_pk_bf16_f32 v25, v26, v27
	global_store_dwordx2 v[20:21], v[24:25], off
	v_lshl_add_u64 v[20:21], v[20:21], 0, s[10:11]
	v_rcp_f32_e32 v64, v57
	s_nop 0
	v_mov_b32_e32 v57, v64
	v_mul_f32_e32 v28, v28, v57
	v_mul_f32_e32 v29, v29, v57
	v_mul_f32_e32 v30, v30, v57
	v_mul_f32_e32 v31, v31, v57
	v_cvt_pk_bf16_f32 v28, v28, v29
	v_cvt_pk_bf16_f32 v29, v30, v31
	global_store_dwordx2 v[20:21], v[28:29], off
	v_lshl_add_u64 v[20:21], v[20:21], 0, s[10:11]
	v_rcp_f32_e32 v64, v58
	s_nop 0
	v_mov_b32_e32 v58, v64
	v_mul_f32_e32 v32, v32, v58
	v_mul_f32_e32 v33, v33, v58
	v_mul_f32_e32 v34, v34, v58
	v_mul_f32_e32 v35, v35, v58
	v_cvt_pk_bf16_f32 v32, v32, v33
	v_cvt_pk_bf16_f32 v33, v34, v35
	global_store_dwordx2 v[20:21], v[32:33], off
	v_lshl_add_u64 v[20:21], v[20:21], 0, s[10:11]
	v_rcp_f32_e32 v64, v59
	s_nop 0
	v_mov_b32_e32 v59, v64
	v_mul_f32_e32 v36, v36, v59
	v_mul_f32_e32 v37, v37, v59
	v_mul_f32_e32 v38, v38, v59
	v_mul_f32_e32 v39, v39, v59
	v_cvt_pk_bf16_f32 v36, v36, v37
	v_cvt_pk_bf16_f32 v37, v38, v39
	global_store_dwordx2 v[20:21], v[36:37], off
	v_lshl_add_u64 v[20:21], v[20:21], 0, s[10:11]
	s_waitcnt vmcnt(4)
; DEV float wave_max(float v) {
; #pragma unroll
;     for (int o = 32; o >= 1; o >>= 1) v = fmaxf(v, __shfl_xor(v, o));
;     return v;
; }
; __global__ void __launch_bounds__(512) hymba_fwd(Params p) {
;     ...
;         const float mx = wave_max(fmaxf(fmaxf(v[0], v[1]), fmaxf(v[2], v[3])));
;         f32x4 e; e[0] = __expf(v[0] - mx); e[1] = __expf(v[1] - mx); e[2] = __expf(v[2] - mx); e[3] = __expf(v[3] - mx);
;         const float inv = 1.f / wave_sum(e[0] + e[1] + e[2] + e[3]);
	v_max_f32_e32 v56, v43, v43
	v_max_f32_e32 v60, v42, v42
	v_max_f32_e32 v56, v60, v56
	v_max3_f32 v56, v40, v41, v56
	v_max_f32_e32 v57, v47, v47
	v_max_f32_e32 v61, v46, v46
	v_max_f32_e32 v57, v61, v57
	v_max3_f32 v57, v44, v45, v57
	v_max_f32_e32 v58, v51, v51
	v_max_f32_e32 v62, v50, v50
	v_max_f32_e32 v58, v62, v58
	v_max3_f32 v58, v48, v49, v58
	v_max_f32_e32 v59, v55, v55
	v_max_f32_e32 v63, v54, v54
	v_max_f32_e32 v59, v63, v59
	v_max3_f32 v59, v52, v53, v59
	ds_bpermute_b32 v60, v8, v56
	ds_bpermute_b32 v61, v8, v57
	ds_bpermute_b32 v62, v8, v58
	ds_bpermute_b32 v63, v8, v59
	s_waitcnt lgkmcnt(3)
	v_max_f32_e32 v60, v60, v60
	v_max_f32_e32 v56, v56, v60
	s_waitcnt lgkmcnt(2)
	v_max_f32_e32 v61, v61, v61
	v_max_f32_e32 v57, v57, v61
	s_waitcnt lgkmcnt(1)
	v_max_f32_e32 v62, v62, v62
	v_max_f32_e32 v58, v58, v62
	s_waitcnt lgkmcnt(0)
	v_max_f32_e32 v63, v63, v63
	v_max_f32_e32 v59, v59, v63
	ds_bpermute_b32 v60, v9, v56
	ds_bpermute_b32 v61, v9, v57
	ds_bpermute_b32 v62, v9, v58
	ds_bpermute_b32 v63, v9, v59
	s_waitcnt lgkmcnt(3)
	v_max_f32_e32 v60, v60, v60
	v_max_f32_e32 v56, v56, v60
	s_waitcnt lgkmcnt(2)
	v_max_f32_e32 v61, v61, v61
	v_max_f32_e32 v57, v57, v61
	s_waitcnt lgkmcnt(1)
	v_max_f32_e32 v62, v62, v62
	v_max_f32_e32 v58, v58, v62
	s_waitcnt lgkmcnt(0)
	v_max_f32_e32 v63, v63, v63
	v_max_f32_e32 v59, v59, v63
	ds_bpermute_b32 v60, v10, v56
	ds_bpermute_b32 v61, v10, v57
	ds_bpermute_b32 v62, v10, v58
	ds_bpermute_b32 v63, v10, v59
	s_waitcnt lgkmcnt(3)
	v_max_f32_e32 v60, v60, v60
	v_max_f32_e32 v56, v56, v60
	s_waitcnt lgkmcnt(2)
	v_max_f32_e32 v61, v61, v61
	v_max_f32_e32 v57, v57, v61
	s_waitcnt lgkmcnt(1)
	v_max_f32_e32 v62, v62, v62
	v_max_f32_e32 v58, v58, v62
	s_waitcnt lgkmcnt(0)
	v_max_f32_e32 v63, v63, v63
	v_max_f32_e32 v59, v59, v63
	ds_bpermute_b32 v60, v11, v56
	ds_bpermute_b32 v61, v11, v57
	ds_bpermute_b32 v62, v11, v58
	ds_bpermute_b32 v63, v11, v59
	s_waitcnt lgkmcnt(3)
	v_max_f32_e32 v60, v60, v60
	v_max_f32_e32 v56, v56, v60
	s_waitcnt lgkmcnt(2)
	v_max_f32_e32 v61, v61, v61
	v_max_f32_e32 v57, v57, v61
	s_waitcnt lgkmcnt(1)
	v_max_f32_e32 v62, v62, v62
	v_max_f32_e32 v58, v58, v62
	s_waitcnt lgkmcnt(0)
	v_max_f32_e32 v63, v63, v63
	v_max_f32_e32 v59, v59, v63
	ds_bpermute_b32 v60, v12, v56
	ds_bpermute_b32 v61, v12, v57
	ds_bpermute_b32 v62, v12, v58
	ds_bpermute_b32 v63, v12, v59
	s_waitcnt lgkmcnt(3)
	v_max_f32_e32 v60, v60, v60
	v_max_f32_e32 v56, v56, v60
	s_waitcnt lgkmcnt(2)
	v_max_f32_e32 v61, v61, v61
	v_max_f32_e32 v57, v57, v61
	s_waitcnt lgkmcnt(1)
	v_max_f32_e32 v62, v62, v62
	v_max_f32_e32 v58, v58, v62
	s_waitcnt lgkmcnt(0)
	v_max_f32_e32 v63, v63, v63
	v_max_f32_e32 v59, v59, v63
	ds_bpermute_b32 v60, v13, v56
	ds_bpermute_b32 v61, v13, v57
	ds_bpermute_b32 v62, v13, v58
	ds_bpermute_b32 v63, v13, v59
	s_waitcnt lgkmcnt(3)
	v_max_f32_e32 v60, v60, v60
	v_max_f32_e32 v56, v56, v60
	s_waitcnt lgkmcnt(2)
	v_max_f32_e32 v61, v61, v61
	v_max_f32_e32 v57, v57, v61
	s_waitcnt lgkmcnt(1)
	v_max_f32_e32 v62, v62, v62
	v_max_f32_e32 v58, v58, v62
	s_waitcnt lgkmcnt(0)
	v_max_f32_e32 v63, v63, v63
	v_max_f32_e32 v59, v59, v63
	v_sub_f32_e32 v40, v40, v56
	v_sub_f32_e32 v41, v41, v56
	v_sub_f32_e32 v42, v42, v56
	v_sub_f32_e32 v43, v43, v56
	v_mul_f32_e32 v40, 0x3fb8aa3b, v40
	v_mul_f32_e32 v41, 0x3fb8aa3b, v41
	v_mul_f32_e32 v42, 0x3fb8aa3b, v42
	v_mul_f32_e32 v43, 0x3fb8aa3b, v43
	v_sub_f32_e32 v44, v44, v57
	v_sub_f32_e32 v45, v45, v57
	v_sub_f32_e32 v46, v46, v57
	v_sub_f32_e32 v47, v47, v57
	v_mul_f32_e32 v44, 0x3fb8aa3b, v44
	v_mul_f32_e32 v45, 0x3fb8aa3b, v45
	v_mul_f32_e32 v46, 0x3fb8aa3b, v46
	v_mul_f32_e32 v47, 0x3fb8aa3b, v47
	v_sub_f32_e32 v48, v48, v58
	v_sub_f32_e32 v49, v49, v58
	v_sub_f32_e32 v50, v50, v58
	v_sub_f32_e32 v51, v51, v58
	v_mul_f32_e32 v48, 0x3fb8aa3b, v48
	v_mul_f32_e32 v49, 0x3fb8aa3b, v49
	v_mul_f32_e32 v50, 0x3fb8aa3b, v50
	v_mul_f32_e32 v51, 0x3fb8aa3b, v51
	v_sub_f32_e32 v52, v52, v59
	v_sub_f32_e32 v53, v53, v59
	v_sub_f32_e32 v54, v54, v59
	v_sub_f32_e32 v55, v55, v59
	v_mul_f32_e32 v52, 0x3fb8aa3b, v52
	v_mul_f32_e32 v53, 0x3fb8aa3b, v53
	v_mul_f32_e32 v54, 0x3fb8aa3b, v54
	v_mul_f32_e32 v55, 0x3fb8aa3b, v55
	v_exp_f32_e32 v40, v40
	v_exp_f32_e32 v41, v41
	v_exp_f32_e32 v42, v42
	v_exp_f32_e32 v43, v43
	v_exp_f32_e32 v44, v44
	v_exp_f32_e32 v45, v45
	v_exp_f32_e32 v46, v46
	v_exp_f32_e32 v47, v47
	v_exp_f32_e32 v48, v48
	v_exp_f32_e32 v49, v49
	v_exp_f32_e32 v50, v50
	v_exp_f32_e32 v51, v51
	v_exp_f32_e32 v52, v52
	v_exp_f32_e32 v53, v53
	v_exp_f32_e32 v54, v54
	v_exp_f32_e32 v55, v55
	v_add_f32_e32 v56, v40, v41
	v_add_f32_e32 v56, v42, v56
	v_add_f32_e32 v56, v43, v56
	v_add_f32_e32 v57, v44, v45
	v_add_f32_e32 v57, v46, v57
	v_add_f32_e32 v57, v47, v57
	v_add_f32_e32 v58, v48, v49
	v_add_f32_e32 v58, v50, v58
	v_add_f32_e32 v58, v51, v58
	v_add_f32_e32 v59, v52, v53
	v_add_f32_e32 v59, v54, v59
	v_add_f32_e32 v59, v55, v59
	ds_bpermute_b32 v60, v8, v56
	ds_bpermute_b32 v61, v8, v57
	ds_bpermute_b32 v62, v8, v58
	ds_bpermute_b32 v63, v8, v59
	s_waitcnt lgkmcnt(3)
; DEV void store_bf4(bf16_t* p, f32x4 v) { uint2 w; w.x = cvt_pk_bf16(v[0], v[1]); w.y = cvt_pk_bf16(v[2], v[3]); *(uint2*)p = w; }
; __global__ void __launch_bounds__(512) hymba_fwd(Params p) {
;     ...
;     for (int r = bid * 8 + wid; r < TP * 4; r += G * 8) {
;         const f32x4 v = __builtin_nontemporal_load((const f32x4*)(sc + (size_t)r * 256 + lane * 4));
;         const float mx = wave_max(fmaxf(fmaxf(v[0], v[1]), fmaxf(v[2], v[3])));
;         f32x4 e; e[0] = __expf(v[0] - mx); e[1] = __expf(v[1] - mx); e[2] = __expf(v[2] - mx); e[3] = __expf(v[3] - mx);
;         const float inv = 1.f / wave_sum(e[0] + e[1] + e[2] + e[3]);
;         store_bf4(pb + (size_t)(r >> 2) * LDP + (r & 3) * 256 + lane * 4, e * inv);
;     }
	v_add_f32_e32 v56, v56, v60
	s_waitcnt lgkmcnt(2)
	v_add_f32_e32 v57, v57, v61
	s_waitcnt lgkmcnt(1)
	v_add_f32_e32 v58, v58, v62
	s_waitcnt lgkmcnt(0)
	v_add_f32_e32 v59, v59, v63
	ds_bpermute_b32 v60, v9, v56
	ds_bpermute_b32 v61, v9, v57
	ds_bpermute_b32 v62, v9, v58
	ds_bpermute_b32 v63, v9, v59
	s_waitcnt lgkmcnt(3)
	v_add_f32_e32 v56, v56, v60
	s_waitcnt lgkmcnt(2)
	v_add_f32_e32 v57, v57, v61
	s_waitcnt lgkmcnt(1)
	v_add_f32_e32 v58, v58, v62
	s_waitcnt lgkmcnt(0)
	v_add_f32_e32 v59, v59, v63
	ds_bpermute_b32 v60, v10, v56
	ds_bpermute_b32 v61, v10, v57
	ds_bpermute_b32 v62, v10, v58
	ds_bpermute_b32 v63, v10, v59
	s_waitcnt lgkmcnt(3)
	v_add_f32_e32 v56, v56, v60
	s_waitcnt lgkmcnt(2)
	v_add_f32_e32 v57, v57, v61
	s_waitcnt lgkmcnt(1)
	v_add_f32_e32 v58, v58, v62
	s_waitcnt lgkmcnt(0)
	v_add_f32_e32 v59, v59, v63
	ds_bpermute_b32 v60, v11, v56
	ds_bpermute_b32 v61, v11, v57
	ds_bpermute_b32 v62, v11, v58
	ds_bpermute_b32 v63, v11, v59
	s_waitcnt lgkmcnt(3)
	v_add_f32_e32 v56, v56, v60
	s_waitcnt lgkmcnt(2)
	v_add_f32_e32 v57, v57, v61
	s_waitcnt lgkmcnt(1)
	v_add_f32_e32 v58, v58, v62
	s_waitcnt lgkmcnt(0)
	v_add_f32_e32 v59, v59, v63
	ds_bpermute_b32 v60, v12, v56
	ds_bpermute_b32 v61, v12, v57
	ds_bpermute_b32 v62, v12, v58
	ds_bpermute_b32 v63, v12, v59
	s_waitcnt lgkmcnt(3)
	v_add_f32_e32 v56, v56, v60
	s_waitcnt lgkmcnt(2)
	v_add_f32_e32 v57, v57, v61
	s_waitcnt lgkmcnt(1)
	v_add_f32_e32 v58, v58, v62
	s_waitcnt lgkmcnt(0)
	v_add_f32_e32 v59, v59, v63
	ds_bpermute_b32 v60, v13, v56
	ds_bpermute_b32 v61, v13, v57
	ds_bpermute_b32 v62, v13, v58
	ds_bpermute_b32 v63, v13, v59
	s_waitcnt lgkmcnt(3)
	v_add_f32_e32 v56, v56, v60
	s_waitcnt lgkmcnt(2)
	v_add_f32_e32 v57, v57, v61
	s_waitcnt lgkmcnt(1)
	v_add_f32_e32 v58, v58, v62
	s_waitcnt lgkmcnt(0)
	v_add_f32_e32 v59, v59, v63
	v_rcp_f32_e32 v64, v56
	s_nop 0
	v_mov_b32_e32 v56, v64
	v_mul_f32_e32 v40, v40, v56
	v_mul_f32_e32 v41, v41, v56
	v_mul_f32_e32 v42, v42, v56
	v_mul_f32_e32 v43, v43, v56
	v_cvt_pk_bf16_f32 v40, v40, v41
	v_cvt_pk_bf16_f32 v41, v42, v43
	global_store_dwordx2 v[20:21], v[40:41], off
	v_lshl_add_u64 v[20:21], v[20:21], 0, s[10:11]
	v_rcp_f32_e32 v64, v57
	s_nop 0
	v_mov_b32_e32 v57, v64
	v_mul_f32_e32 v44, v44, v57
	v_mul_f32_e32 v45, v45, v57
	v_mul_f32_e32 v46, v46, v57
	v_mul_f32_e32 v47, v47, v57
	v_cvt_pk_bf16_f32 v44, v44, v45
	v_cvt_pk_bf16_f32 v45, v46, v47
	global_store_dwordx2 v[20:21], v[44:45], off
	v_lshl_add_u64 v[20:21], v[20:21], 0, s[10:11]
	v_rcp_f32_e32 v64, v58
	s_nop 0
	v_mov_b32_e32 v58, v64
	v_mul_f32_e32 v48, v48, v58
	v_mul_f32_e32 v49, v49, v58
	v_mul_f32_e32 v50, v50, v58
	v_mul_f32_e32 v51, v51, v58
	v_cvt_pk_bf16_f32 v48, v48, v49
	v_cvt_pk_bf16_f32 v49, v50, v51
	global_store_dwordx2 v[20:21], v[48:49], off
	v_lshl_add_u64 v[20:21], v[20:21], 0, s[10:11]
	v_rcp_f32_e32 v64, v59
	s_nop 0
	v_mov_b32_e32 v59, v64
	v_mul_f32_e32 v52, v52, v59
	v_mul_f32_e32 v53, v53, v59
	v_mul_f32_e32 v54, v54, v59
	v_mul_f32_e32 v55, v55, v59
	v_cvt_pk_bf16_f32 v52, v52, v53
	v_cvt_pk_bf16_f32 v53, v54, v55
	global_store_dwordx2 v[20:21], v[52:53], off
	v_lshl_add_u64 v[20:21], v[20:21], 0, s[10:11]
	s_waitcnt vmcnt(0)
	s_barrier
	s_mov_b64 s[6:7], 0x20f39000
	v_lshl_add_u64 v[86:87], v[158:159], 0, s[6:7]
	s_branch .Lp10_guard
